# loop-edge: K-loop counter/pointer bumps and exit compare moved ahead of the last barrier (end of last load segment); only the branch stays behind the back-edge barrier
# speedup vs baseline: 1.0017x; 1.0017x over previous
.Lmy_prio_skip0:
.LBB0_116:
	ds_read_b128 v[128:131], v229
	ds_read_b128 v[132:135], v229 offset:1024
	ds_read_b128 v[136:139], v229 offset:2048
	ds_read_b128 v[140:143], v229 offset:3072
	ds_read_b128 v[144:147], v230
	ds_read_b128 v[148:151], v230 offset:1024
	ds_read_b128 v[152:155], v230 offset:2048
	ds_read_b128 v[156:159], v230 offset:3072
	s_add_u32 vcc_lo, s94, 0x100
	s_addc_u32 vcc_hi, s95, 0
	s_cmp_eq_u32 s37, 60
	s_cselect_b32 s53, s89, vcc_hi
	s_cselect_b32 s52, s93, vcc_lo
	s_cselect_b32 s97, s85, s36
	s_cselect_b32 s96, s34, s35
	s_add_i32 m0, s67, 0xc000
	ds_read_b128 v[160:163], v231
	ds_read_b128 v[164:167], v231 offset:1024
	ds_read_b128 v[186:189], v231 offset:2048
	ds_read_b128 v[190:193], v231 offset:3072
	ds_read_b128 v[194:197], v231 offset:4096
	ds_read_b128 v[198:201], v231 offset:5120
	ds_read_b128 v[202:205], v231 offset:6144
	ds_read_b128 v[206:209], v231 offset:7168
	global_load_lds_dwordx4 v178, s[94:95]
	s_add_i32 m0, s67, 0xe000
	s_nop 0
	global_load_lds_dwordx4 v180, s[94:95]
	s_waitcnt vmcnt(8)
	s_waitcnt lgkmcnt(0)
	s_barrier
	s_waitcnt lgkmcnt(0)
	v_mfma_f32_16x16x32_bf16 v[124:127], v[128:131], v[160:163], v[124:127]
	v_mfma_f32_16x16x32_bf16 v[120:123], v[136:139], v[160:163], v[120:123]
	v_mfma_f32_16x16x32_bf16 v[112:115], v[128:131], v[186:189], v[112:115]
	v_mfma_f32_16x16x32_bf16 v[104:107], v[136:139], v[186:189], v[104:107]
	v_mfma_f32_16x16x32_bf16 v[96:99], v[128:131], v[194:197], v[96:99]
	v_mfma_f32_16x16x32_bf16 v[88:91], v[136:139], v[194:197], v[88:91]
	v_mfma_f32_16x16x32_bf16 v[80:83], v[128:131], v[202:205], v[80:83]
	v_mfma_f32_16x16x32_bf16 v[72:75], v[136:139], v[202:205], v[72:75]
	v_mfma_f32_16x16x32_bf16 v[124:127], v[132:135], v[164:167], v[124:127]
	v_mfma_f32_16x16x32_bf16 v[120:123], v[140:143], v[164:167], v[120:123]
	v_mfma_f32_16x16x32_bf16 v[112:115], v[132:135], v[190:193], v[112:115]
	v_mfma_f32_16x16x32_bf16 v[104:107], v[140:143], v[190:193], v[104:107]
	v_mfma_f32_16x16x32_bf16 v[96:99], v[132:135], v[198:201], v[96:99]
	v_mfma_f32_16x16x32_bf16 v[88:91], v[140:143], v[198:201], v[88:91]
	v_mfma_f32_16x16x32_bf16 v[80:83], v[132:135], v[206:209], v[80:83]
	v_mfma_f32_16x16x32_bf16 v[72:75], v[140:143], v[206:209], v[72:75]
	v_mfma_f32_16x16x32_bf16 v[116:119], v[144:147], v[160:163], v[116:119]
	v_mfma_f32_16x16x32_bf16 v[108:111], v[152:155], v[160:163], v[108:111]
	v_mfma_f32_16x16x32_bf16 v[100:103], v[144:147], v[186:189], v[100:103]
	v_mfma_f32_16x16x32_bf16 v[92:95], v[152:155], v[186:189], v[92:95]
	v_mfma_f32_16x16x32_bf16 v[84:87], v[144:147], v[194:197], v[84:87]
	v_mfma_f32_16x16x32_bf16 v[76:79], v[152:155], v[194:197], v[76:79]
	v_mfma_f32_16x16x32_bf16 v[68:71], v[144:147], v[202:205], v[68:71]
	v_mfma_f32_16x16x32_bf16 v[64:67], v[152:155], v[202:205], v[64:67]
	v_mfma_f32_16x16x32_bf16 v[116:119], v[148:151], v[164:167], v[116:119]
	v_mfma_f32_16x16x32_bf16 v[108:111], v[156:159], v[164:167], v[108:111]
	v_mfma_f32_16x16x32_bf16 v[100:103], v[148:151], v[190:193], v[100:103]
	v_mfma_f32_16x16x32_bf16 v[92:95], v[156:159], v[190:193], v[92:95]
	v_mfma_f32_16x16x32_bf16 v[84:87], v[148:151], v[198:201], v[84:87]
	v_mfma_f32_16x16x32_bf16 v[76:79], v[156:159], v[198:201], v[76:79]
	v_mfma_f32_16x16x32_bf16 v[68:71], v[148:151], v[206:209], v[68:71]
	v_mfma_f32_16x16x32_bf16 v[64:67], v[156:159], v[206:209], v[64:67]
	s_barrier
	s_add_i32 s38, s81, s91
	s_mov_b32 m0, s38
	ds_read_b128 v[160:163], v231 offset:16384
	ds_read_b128 v[164:167], v231 offset:17408
	ds_read_b128 v[186:189], v231 offset:18432
	ds_read_b128 v[190:193], v231 offset:19456
	ds_read_b128 v[194:197], v231 offset:20480
	ds_read_b128 v[198:201], v231 offset:21504
	ds_read_b128 v[202:205], v231 offset:22528
	ds_read_b128 v[206:209], v231 offset:23552
	global_load_lds_dwordx4 v170, s[96:97]
	s_add_i32 m0, s38, 0x2000
	s_add_u32 s38, s96, 0x100000
	s_addc_u32 s39, s97, 0
	s_add_i32 s40, s14, s91
	global_load_lds_dwordx4 v174, s[96:97]
	s_mov_b32 m0, s40
	global_load_lds_dwordx4 v170, s[38:39]
	s_add_i32 m0, s40, 0x2000
	s_nop 0
	global_load_lds_dwordx4 v174, s[38:39]
	s_mov_b32 m0, s67
	s_nop 0
	global_load_lds_dwordx4 v168, s[52:53]
	s_mov_b32 m0, s16
	s_nop 0
	global_load_lds_dwordx4 v172, s[52:53]
	s_waitcnt vmcnt(8)
	s_waitcnt lgkmcnt(0)
	s_barrier
	s_waitcnt lgkmcnt(0)
	v_mfma_f32_16x16x32_bf16 v[60:63], v[128:131], v[160:163], v[60:63]
	v_mfma_f32_16x16x32_bf16 v[56:59], v[136:139], v[160:163], v[56:59]
	v_mfma_f32_16x16x32_bf16 v[44:47], v[128:131], v[186:189], v[44:47]
	v_mfma_f32_16x16x32_bf16 v[40:43], v[136:139], v[186:189], v[40:43]
	v_mfma_f32_16x16x32_bf16 v[28:31], v[128:131], v[194:197], v[28:31]
	v_mfma_f32_16x16x32_bf16 v[24:27], v[136:139], v[194:197], v[24:27]
	v_mfma_f32_16x16x32_bf16 v[12:15], v[128:131], v[202:205], v[12:15]
	v_mfma_f32_16x16x32_bf16 v[8:11], v[136:139], v[202:205], v[8:11]
	v_mfma_f32_16x16x32_bf16 v[60:63], v[132:135], v[164:167], v[60:63]
	v_mfma_f32_16x16x32_bf16 v[56:59], v[140:143], v[164:167], v[56:59]
	v_mfma_f32_16x16x32_bf16 v[44:47], v[132:135], v[190:193], v[44:47]
	v_mfma_f32_16x16x32_bf16 v[40:43], v[140:143], v[190:193], v[40:43]
	v_mfma_f32_16x16x32_bf16 v[28:31], v[132:135], v[198:201], v[28:31]
	v_mfma_f32_16x16x32_bf16 v[24:27], v[140:143], v[198:201], v[24:27]
	v_mfma_f32_16x16x32_bf16 v[12:15], v[132:135], v[206:209], v[12:15]
	v_mfma_f32_16x16x32_bf16 v[8:11], v[140:143], v[206:209], v[8:11]
	v_mfma_f32_16x16x32_bf16 v[52:55], v[144:147], v[160:163], v[52:55]
	v_mfma_f32_16x16x32_bf16 v[48:51], v[152:155], v[160:163], v[48:51]
	v_mfma_f32_16x16x32_bf16 v[36:39], v[144:147], v[186:189], v[36:39]
	v_mfma_f32_16x16x32_bf16 v[32:35], v[152:155], v[186:189], v[32:35]
	v_mfma_f32_16x16x32_bf16 v[20:23], v[144:147], v[194:197], v[20:23]
	v_mfma_f32_16x16x32_bf16 v[16:19], v[152:155], v[194:197], v[16:19]
	v_mfma_f32_16x16x32_bf16 v[4:7], v[144:147], v[202:205], v[4:7]
	v_mfma_f32_16x16x32_bf16 v[0:3], v[152:155], v[202:205], v[0:3]
	v_mfma_f32_16x16x32_bf16 v[52:55], v[148:151], v[164:167], v[52:55]
	v_mfma_f32_16x16x32_bf16 v[48:51], v[156:159], v[164:167], v[48:51]
	v_mfma_f32_16x16x32_bf16 v[36:39], v[148:151], v[190:193], v[36:39]
	v_mfma_f32_16x16x32_bf16 v[32:35], v[156:159], v[190:193], v[32:35]
	v_mfma_f32_16x16x32_bf16 v[20:23], v[148:151], v[198:201], v[20:23]
	v_mfma_f32_16x16x32_bf16 v[16:19], v[156:159], v[198:201], v[16:19]
	v_mfma_f32_16x16x32_bf16 v[4:7], v[148:151], v[206:209], v[4:7]
	v_mfma_f32_16x16x32_bf16 v[0:3], v[156:159], v[206:209], v[0:3]
	s_barrier
	s_add_i32 s40, 0, 0x18000
	s_add_i32 s41, 0, 0x1c000
	v_add_u32_e32 v140, s40, v225
	v_add_u32_e32 v156, s41, v225
	ds_read_b128 v[128:131], v140
	ds_read_b128 v[132:135], v140 offset:1024
	ds_read_b128 v[136:139], v140 offset:2048
	ds_read_b128 v[140:143], v140 offset:3072
	ds_read_b128 v[144:147], v156
	ds_read_b128 v[148:151], v156 offset:1024
	ds_read_b128 v[152:155], v156 offset:2048
	ds_read_b128 v[156:159], v156 offset:3072
	s_add_u32 s38, s52, 0x100000
	s_addc_u32 s39, s53, 0
	s_mov_b32 m0, s17
	ds_read_b128 v[160:163], v231 offset:32768
	ds_read_b128 v[164:167], v231 offset:33792
	ds_read_b128 v[186:189], v231 offset:34816
	ds_read_b128 v[190:193], v231 offset:35840
	ds_read_b128 v[194:197], v231 offset:36864
	ds_read_b128 v[198:201], v231 offset:37888
	ds_read_b128 v[202:205], v231 offset:38912
	ds_read_b128 v[206:209], v231 offset:39936
	global_load_lds_dwordx4 v168, s[38:39]
	s_mov_b32 m0, s10
	s_nop 0
	global_load_lds_dwordx4 v172, s[38:39]
	s_waitcnt vmcnt(8)
	s_waitcnt lgkmcnt(0)
	s_barrier
	s_waitcnt lgkmcnt(0)
	v_mfma_f32_16x16x32_bf16 v[124:127], v[128:131], v[160:163], v[124:127]
	v_mfma_f32_16x16x32_bf16 v[120:123], v[136:139], v[160:163], v[120:123]
	v_mfma_f32_16x16x32_bf16 v[112:115], v[128:131], v[186:189], v[112:115]
	v_mfma_f32_16x16x32_bf16 v[104:107], v[136:139], v[186:189], v[104:107]
	v_mfma_f32_16x16x32_bf16 v[96:99], v[128:131], v[194:197], v[96:99]
	v_mfma_f32_16x16x32_bf16 v[88:91], v[136:139], v[194:197], v[88:91]
	v_mfma_f32_16x16x32_bf16 v[80:83], v[128:131], v[202:205], v[80:83]
	v_mfma_f32_16x16x32_bf16 v[72:75], v[136:139], v[202:205], v[72:75]
	v_mfma_f32_16x16x32_bf16 v[124:127], v[132:135], v[164:167], v[124:127]
	v_mfma_f32_16x16x32_bf16 v[120:123], v[140:143], v[164:167], v[120:123]
	v_mfma_f32_16x16x32_bf16 v[112:115], v[132:135], v[190:193], v[112:115]
	v_mfma_f32_16x16x32_bf16 v[104:107], v[140:143], v[190:193], v[104:107]
	v_mfma_f32_16x16x32_bf16 v[96:99], v[132:135], v[198:201], v[96:99]
	v_mfma_f32_16x16x32_bf16 v[88:91], v[140:143], v[198:201], v[88:91]
	v_mfma_f32_16x16x32_bf16 v[80:83], v[132:135], v[206:209], v[80:83]
	v_mfma_f32_16x16x32_bf16 v[72:75], v[140:143], v[206:209], v[72:75]
	v_mfma_f32_16x16x32_bf16 v[116:119], v[144:147], v[160:163], v[116:119]
	v_mfma_f32_16x16x32_bf16 v[108:111], v[152:155], v[160:163], v[108:111]
	v_mfma_f32_16x16x32_bf16 v[100:103], v[144:147], v[186:189], v[100:103]
	v_mfma_f32_16x16x32_bf16 v[92:95], v[152:155], v[186:189], v[92:95]
	v_mfma_f32_16x16x32_bf16 v[84:87], v[144:147], v[194:197], v[84:87]
	v_mfma_f32_16x16x32_bf16 v[76:79], v[152:155], v[194:197], v[76:79]
	v_mfma_f32_16x16x32_bf16 v[68:71], v[144:147], v[202:205], v[68:71]
	v_mfma_f32_16x16x32_bf16 v[64:67], v[152:155], v[202:205], v[64:67]
	v_mfma_f32_16x16x32_bf16 v[116:119], v[148:151], v[164:167], v[116:119]
	v_mfma_f32_16x16x32_bf16 v[108:111], v[156:159], v[164:167], v[108:111]
	v_mfma_f32_16x16x32_bf16 v[100:103], v[148:151], v[190:193], v[100:103]
	v_mfma_f32_16x16x32_bf16 v[92:95], v[156:159], v[190:193], v[92:95]
	v_mfma_f32_16x16x32_bf16 v[84:87], v[148:151], v[198:201], v[84:87]
	v_mfma_f32_16x16x32_bf16 v[76:79], v[156:159], v[198:201], v[76:79]
	v_mfma_f32_16x16x32_bf16 v[68:71], v[148:151], v[206:209], v[68:71]
	v_mfma_f32_16x16x32_bf16 v[64:67], v[156:159], v[206:209], v[64:67]
	s_barrier
	s_add_i32 s38, s40, s91
	s_mov_b32 m0, s38
	ds_read_b128 v[160:163], v231 offset:49152
	ds_read_b128 v[164:167], v231 offset:50176
	ds_read_b128 v[186:189], v231 offset:51200
	ds_read_b128 v[190:193], v231 offset:52224
	ds_read_b128 v[194:197], v231 offset:53248
	ds_read_b128 v[198:201], v231 offset:54272
	ds_read_b128 v[202:205], v231 offset:55296
	ds_read_b128 v[206:209], v231 offset:56320
	s_add_u32 s100, s96, 0x80
	s_addc_u32 s101, s97, 0
	global_load_lds_dwordx4 v170, s[100:101]
	s_add_i32 m0, s38, 0x2000
	s_add_u32 s38, s96, 0x100080
	s_addc_u32 s39, s97, 0
	s_add_i32 s40, s41, s91
	s_add_u32 s100, s96, 0x80
	s_addc_u32 s101, s97, 0
	global_load_lds_dwordx4 v174, s[100:101]
	s_mov_b32 m0, s40
	s_nop 0
	global_load_lds_dwordx4 v170, s[38:39]
	s_add_i32 m0, s40, 0x2000
	s_nop 0
	global_load_lds_dwordx4 v174, s[38:39]
	s_mov_b32 m0, s13
	s_nop 0
	s_add_u32 s100, s52, 0x80
	s_addc_u32 s101, s53, 0
	global_load_lds_dwordx4 v168, s[100:101]
	s_mov_b32 m0, s77
	s_nop 0
	s_add_u32 s100, s52, 0x80
	s_addc_u32 s101, s53, 0
	global_load_lds_dwordx4 v172, s[100:101]
	s_add_i32 s37, s37, 2
	s_add_u32 s35, s35, 0x100
	s_addc_u32 s36, s36, 0
	s_cmp_gt_u32 s37, 61
	s_waitcnt vmcnt(8)
	s_waitcnt lgkmcnt(0)
	s_barrier
	s_waitcnt lgkmcnt(0)
	v_mfma_f32_16x16x32_bf16 v[60:63], v[128:131], v[160:163], v[60:63]
	v_mfma_f32_16x16x32_bf16 v[56:59], v[136:139], v[160:163], v[56:59]
	v_mfma_f32_16x16x32_bf16 v[44:47], v[128:131], v[186:189], v[44:47]
	v_mfma_f32_16x16x32_bf16 v[40:43], v[136:139], v[186:189], v[40:43]
	v_mfma_f32_16x16x32_bf16 v[28:31], v[128:131], v[194:197], v[28:31]
	v_mfma_f32_16x16x32_bf16 v[24:27], v[136:139], v[194:197], v[24:27]
	v_mfma_f32_16x16x32_bf16 v[12:15], v[128:131], v[202:205], v[12:15]
	v_mfma_f32_16x16x32_bf16 v[8:11], v[136:139], v[202:205], v[8:11]
	v_mfma_f32_16x16x32_bf16 v[60:63], v[132:135], v[164:167], v[60:63]
	v_mfma_f32_16x16x32_bf16 v[56:59], v[140:143], v[164:167], v[56:59]
	v_mfma_f32_16x16x32_bf16 v[44:47], v[132:135], v[190:193], v[44:47]
	v_mfma_f32_16x16x32_bf16 v[40:43], v[140:143], v[190:193], v[40:43]
	v_mfma_f32_16x16x32_bf16 v[28:31], v[132:135], v[198:201], v[28:31]
	v_mfma_f32_16x16x32_bf16 v[24:27], v[140:143], v[198:201], v[24:27]
	v_mfma_f32_16x16x32_bf16 v[12:15], v[132:135], v[206:209], v[12:15]
	v_mfma_f32_16x16x32_bf16 v[8:11], v[140:143], v[206:209], v[8:11]
	v_mfma_f32_16x16x32_bf16 v[52:55], v[144:147], v[160:163], v[52:55]
	v_mfma_f32_16x16x32_bf16 v[48:51], v[152:155], v[160:163], v[48:51]
	v_mfma_f32_16x16x32_bf16 v[36:39], v[144:147], v[186:189], v[36:39]
	v_mfma_f32_16x16x32_bf16 v[32:35], v[152:155], v[186:189], v[32:35]
	v_mfma_f32_16x16x32_bf16 v[20:23], v[144:147], v[194:197], v[20:23]
	v_mfma_f32_16x16x32_bf16 v[16:19], v[152:155], v[194:197], v[16:19]
	v_mfma_f32_16x16x32_bf16 v[4:7], v[144:147], v[202:205], v[4:7]
	v_mfma_f32_16x16x32_bf16 v[0:3], v[152:155], v[202:205], v[0:3]
	v_mfma_f32_16x16x32_bf16 v[52:55], v[148:151], v[164:167], v[52:55]
	v_mfma_f32_16x16x32_bf16 v[48:51], v[156:159], v[164:167], v[48:51]
	v_mfma_f32_16x16x32_bf16 v[36:39], v[148:151], v[190:193], v[36:39]
	v_mfma_f32_16x16x32_bf16 v[32:35], v[156:159], v[190:193], v[32:35]
	v_mfma_f32_16x16x32_bf16 v[20:23], v[148:151], v[198:201], v[20:23]
	v_mfma_f32_16x16x32_bf16 v[16:19], v[156:159], v[198:201], v[16:19]
	v_mfma_f32_16x16x32_bf16 v[4:7], v[148:151], v[206:209], v[4:7]
	v_mfma_f32_16x16x32_bf16 v[0:3], v[156:159], v[206:209], v[0:3]
	s_barrier
	s_mov_b64 s[94:95], vcc
	s_cbranch_scc0 .LBB0_116
	s_setprio 0
	s_and_b64 vcc, exec, s[64:65]
	s_cbranch_vccz .LBB0_119
	s_barrier

.Lmy_prio_skip1:
.LBB0_521:
	ds_read_b128 v[152:155], v149
	ds_read_b128 v[156:159], v149 offset:1024
	ds_read_b128 v[160:163], v149 offset:2048
	ds_read_b128 v[164:167], v149 offset:3072
	ds_read_b128 v[168:171], v150
	ds_read_b128 v[172:175], v150 offset:1024
	ds_read_b128 v[176:179], v150 offset:2048
	ds_read_b128 v[180:183], v150 offset:3072
	s_add_u32 s37, s46, 0xfff80080
	s_addc_u32 s38, s47, -1
	s_cmp_eq_u32 s36, 28
	s_cselect_b32 s51, s13, s38
	s_cselect_b32 s50, s64, s37
	s_cselect_b32 s49, s11, s35
	s_cselect_b32 s48, s65, s34
	s_add_i32 m0, s17, 0xc000
	ds_read_b128 v[184:187], v151
	ds_read_b128 v[188:191], v151 offset:1024
	ds_read_b128 v[192:195], v151 offset:2048
	ds_read_b128 v[196:199], v151 offset:3072
	ds_read_b128 v[200:203], v151 offset:4096
	ds_read_b128 v[204:207], v151 offset:5120
	ds_read_b128 v[208:211], v151 offset:6144
	ds_read_b128 v[212:215], v151 offset:7168
	global_load_lds_dwordx4 v136, s[46:47]
	s_add_i32 m0, s17, 0xe000
	s_nop 0
	global_load_lds_dwordx4 v138, s[46:47]
	s_waitcnt vmcnt(8)
	s_waitcnt lgkmcnt(0)
	s_barrier
	s_waitcnt lgkmcnt(0)
	v_mfma_f32_16x16x32_bf16 v[124:127], v[152:155], v[184:187], v[124:127]
	v_mfma_f32_16x16x32_bf16 v[120:123], v[160:163], v[184:187], v[120:123]
	v_mfma_f32_16x16x32_bf16 v[116:119], v[152:155], v[192:195], v[116:119]
	v_mfma_f32_16x16x32_bf16 v[108:111], v[160:163], v[192:195], v[108:111]
	v_mfma_f32_16x16x32_bf16 v[100:103], v[152:155], v[200:203], v[100:103]
	v_mfma_f32_16x16x32_bf16 v[92:95], v[160:163], v[200:203], v[92:95]
	v_mfma_f32_16x16x32_bf16 v[84:87], v[152:155], v[208:211], v[84:87]
	v_mfma_f32_16x16x32_bf16 v[76:79], v[160:163], v[208:211], v[76:79]
	v_mfma_f32_16x16x32_bf16 v[124:127], v[156:159], v[188:191], v[124:127]
	v_mfma_f32_16x16x32_bf16 v[120:123], v[164:167], v[188:191], v[120:123]
	v_mfma_f32_16x16x32_bf16 v[116:119], v[156:159], v[196:199], v[116:119]
	v_mfma_f32_16x16x32_bf16 v[108:111], v[164:167], v[196:199], v[108:111]
	v_mfma_f32_16x16x32_bf16 v[100:103], v[156:159], v[204:207], v[100:103]
	v_mfma_f32_16x16x32_bf16 v[92:95], v[164:167], v[204:207], v[92:95]
	v_mfma_f32_16x16x32_bf16 v[84:87], v[156:159], v[212:215], v[84:87]
	v_mfma_f32_16x16x32_bf16 v[76:79], v[164:167], v[212:215], v[76:79]
	v_mfma_f32_16x16x32_bf16 v[112:115], v[168:171], v[184:187], v[112:115]
	v_mfma_f32_16x16x32_bf16 v[104:107], v[176:179], v[184:187], v[104:107]
	v_mfma_f32_16x16x32_bf16 v[96:99], v[168:171], v[192:195], v[96:99]
	v_mfma_f32_16x16x32_bf16 v[88:91], v[176:179], v[192:195], v[88:91]
	v_mfma_f32_16x16x32_bf16 v[80:83], v[168:171], v[200:203], v[80:83]
	v_mfma_f32_16x16x32_bf16 v[72:75], v[176:179], v[200:203], v[72:75]
	v_mfma_f32_16x16x32_bf16 v[68:71], v[168:171], v[208:211], v[68:71]
	v_mfma_f32_16x16x32_bf16 v[64:67], v[176:179], v[208:211], v[64:67]
	v_mfma_f32_16x16x32_bf16 v[112:115], v[172:175], v[188:191], v[112:115]
	v_mfma_f32_16x16x32_bf16 v[104:107], v[180:183], v[188:191], v[104:107]
	v_mfma_f32_16x16x32_bf16 v[96:99], v[172:175], v[196:199], v[96:99]
	v_mfma_f32_16x16x32_bf16 v[88:91], v[180:183], v[196:199], v[88:91]
	v_mfma_f32_16x16x32_bf16 v[80:83], v[172:175], v[204:207], v[80:83]
	v_mfma_f32_16x16x32_bf16 v[72:75], v[180:183], v[204:207], v[72:75]
	v_mfma_f32_16x16x32_bf16 v[68:71], v[172:175], v[212:215], v[68:71]
	v_mfma_f32_16x16x32_bf16 v[64:67], v[180:183], v[212:215], v[64:67]
	s_barrier
	s_add_i32 s37, s61, s53
	s_mov_b32 m0, s37
	ds_read_b128 v[184:187], v151 offset:16384
	ds_read_b128 v[188:191], v151 offset:17408
	ds_read_b128 v[192:195], v151 offset:18432
	ds_read_b128 v[196:199], v151 offset:19456
	ds_read_b128 v[200:203], v151 offset:20480
	ds_read_b128 v[204:207], v151 offset:21504
	ds_read_b128 v[208:211], v151 offset:22528
	ds_read_b128 v[212:215], v151 offset:23552
	global_load_lds_dwordx4 v130, s[48:49]
	s_add_i32 m0, s37, 0x2000
	s_add_u32 s38, s48, 0x20000
	s_addc_u32 s39, s49, 0
	s_add_i32 s37, s62, s53
	global_load_lds_dwordx4 v134, s[48:49]
	s_mov_b32 m0, s37
	global_load_lds_dwordx4 v130, s[38:39]
	s_add_i32 m0, s37, 0x2000
	s_nop 0
	global_load_lds_dwordx4 v134, s[38:39]
	s_mov_b32 m0, s17
	s_nop 0
	global_load_lds_dwordx4 v128, s[50:51]
	s_mov_b32 m0, s54
	s_nop 0
	global_load_lds_dwordx4 v132, s[50:51]
	s_waitcnt vmcnt(8)
	s_waitcnt lgkmcnt(0)
	s_barrier
	s_waitcnt lgkmcnt(0)
	v_mfma_f32_16x16x32_bf16 v[60:63], v[152:155], v[184:187], v[60:63]
	v_mfma_f32_16x16x32_bf16 v[56:59], v[160:163], v[184:187], v[56:59]
	v_mfma_f32_16x16x32_bf16 v[52:55], v[152:155], v[192:195], v[52:55]
	v_mfma_f32_16x16x32_bf16 v[44:47], v[160:163], v[192:195], v[44:47]
	v_mfma_f32_16x16x32_bf16 v[36:39], v[152:155], v[200:203], v[36:39]
	v_mfma_f32_16x16x32_bf16 v[28:31], v[160:163], v[200:203], v[28:31]
	v_mfma_f32_16x16x32_bf16 v[20:23], v[152:155], v[208:211], v[20:23]
	v_mfma_f32_16x16x32_bf16 v[12:15], v[160:163], v[208:211], v[12:15]
	v_mfma_f32_16x16x32_bf16 v[60:63], v[156:159], v[188:191], v[60:63]
	v_mfma_f32_16x16x32_bf16 v[56:59], v[164:167], v[188:191], v[56:59]
	v_mfma_f32_16x16x32_bf16 v[52:55], v[156:159], v[196:199], v[52:55]
	v_mfma_f32_16x16x32_bf16 v[44:47], v[164:167], v[196:199], v[44:47]
	v_mfma_f32_16x16x32_bf16 v[36:39], v[156:159], v[204:207], v[36:39]
	v_mfma_f32_16x16x32_bf16 v[28:31], v[164:167], v[204:207], v[28:31]
	v_mfma_f32_16x16x32_bf16 v[20:23], v[156:159], v[212:215], v[20:23]
	v_mfma_f32_16x16x32_bf16 v[12:15], v[164:167], v[212:215], v[12:15]
	v_mfma_f32_16x16x32_bf16 v[48:51], v[168:171], v[184:187], v[48:51]
	v_mfma_f32_16x16x32_bf16 v[40:43], v[176:179], v[184:187], v[40:43]
	v_mfma_f32_16x16x32_bf16 v[32:35], v[168:171], v[192:195], v[32:35]
	v_mfma_f32_16x16x32_bf16 v[24:27], v[176:179], v[192:195], v[24:27]
	v_mfma_f32_16x16x32_bf16 v[16:19], v[168:171], v[200:203], v[16:19]
	v_mfma_f32_16x16x32_bf16 v[8:11], v[176:179], v[200:203], v[8:11]
	v_mfma_f32_16x16x32_bf16 v[4:7], v[168:171], v[208:211], v[4:7]
	v_mfma_f32_16x16x32_bf16 v[0:3], v[176:179], v[208:211], v[0:3]
	v_mfma_f32_16x16x32_bf16 v[48:51], v[172:175], v[188:191], v[48:51]
	v_mfma_f32_16x16x32_bf16 v[40:43], v[180:183], v[188:191], v[40:43]
	v_mfma_f32_16x16x32_bf16 v[32:35], v[172:175], v[196:199], v[32:35]
	v_mfma_f32_16x16x32_bf16 v[24:27], v[180:183], v[196:199], v[24:27]
	v_mfma_f32_16x16x32_bf16 v[16:19], v[172:175], v[204:207], v[16:19]
	v_mfma_f32_16x16x32_bf16 v[8:11], v[180:183], v[204:207], v[8:11]
	v_mfma_f32_16x16x32_bf16 v[4:7], v[172:175], v[212:215], v[4:7]
	v_mfma_f32_16x16x32_bf16 v[0:3], v[180:183], v[212:215], v[0:3]
	s_barrier
	s_add_i32 s37, 0, 0x18000
	s_add_i32 s40, 0, 0x1c000
	v_add_u32_e32 v164, s37, v147
	v_add_u32_e32 v180, s40, v147
	ds_read_b128 v[152:155], v164
	ds_read_b128 v[156:159], v164 offset:1024
	ds_read_b128 v[160:163], v164 offset:2048
	ds_read_b128 v[164:167], v164 offset:3072
	ds_read_b128 v[168:171], v180
	ds_read_b128 v[172:175], v180 offset:1024
	ds_read_b128 v[176:179], v180 offset:2048
	ds_read_b128 v[180:183], v180 offset:3072
	s_add_u32 s38, s50, 0x80000
	s_addc_u32 s39, s51, 0
	s_mov_b32 m0, s55
	ds_read_b128 v[184:187], v151 offset:32768
	ds_read_b128 v[188:191], v151 offset:33792
	ds_read_b128 v[192:195], v151 offset:34816
	ds_read_b128 v[196:199], v151 offset:35840
	ds_read_b128 v[200:203], v151 offset:36864
	ds_read_b128 v[204:207], v151 offset:37888
	ds_read_b128 v[208:211], v151 offset:38912
	ds_read_b128 v[212:215], v151 offset:39936
	global_load_lds_dwordx4 v128, s[38:39]
	s_mov_b32 m0, s56
	s_nop 0
	global_load_lds_dwordx4 v132, s[38:39]
	s_waitcnt vmcnt(8)
	s_waitcnt lgkmcnt(0)
	s_barrier
	s_waitcnt lgkmcnt(0)
	v_mfma_f32_16x16x32_bf16 v[124:127], v[152:155], v[184:187], v[124:127]
	v_mfma_f32_16x16x32_bf16 v[120:123], v[160:163], v[184:187], v[120:123]
	v_mfma_f32_16x16x32_bf16 v[116:119], v[152:155], v[192:195], v[116:119]
	v_mfma_f32_16x16x32_bf16 v[108:111], v[160:163], v[192:195], v[108:111]
	v_mfma_f32_16x16x32_bf16 v[100:103], v[152:155], v[200:203], v[100:103]
	v_mfma_f32_16x16x32_bf16 v[92:95], v[160:163], v[200:203], v[92:95]
	v_mfma_f32_16x16x32_bf16 v[84:87], v[152:155], v[208:211], v[84:87]
	v_mfma_f32_16x16x32_bf16 v[76:79], v[160:163], v[208:211], v[76:79]
	v_mfma_f32_16x16x32_bf16 v[124:127], v[156:159], v[188:191], v[124:127]
	v_mfma_f32_16x16x32_bf16 v[120:123], v[164:167], v[188:191], v[120:123]
	v_mfma_f32_16x16x32_bf16 v[116:119], v[156:159], v[196:199], v[116:119]
	v_mfma_f32_16x16x32_bf16 v[108:111], v[164:167], v[196:199], v[108:111]
	v_mfma_f32_16x16x32_bf16 v[100:103], v[156:159], v[204:207], v[100:103]
	v_mfma_f32_16x16x32_bf16 v[92:95], v[164:167], v[204:207], v[92:95]
	v_mfma_f32_16x16x32_bf16 v[84:87], v[156:159], v[212:215], v[84:87]
	v_mfma_f32_16x16x32_bf16 v[76:79], v[164:167], v[212:215], v[76:79]
	v_mfma_f32_16x16x32_bf16 v[112:115], v[168:171], v[184:187], v[112:115]
	v_mfma_f32_16x16x32_bf16 v[104:107], v[176:179], v[184:187], v[104:107]
	v_mfma_f32_16x16x32_bf16 v[96:99], v[168:171], v[192:195], v[96:99]
	v_mfma_f32_16x16x32_bf16 v[88:91], v[176:179], v[192:195], v[88:91]
	v_mfma_f32_16x16x32_bf16 v[80:83], v[168:171], v[200:203], v[80:83]
	v_mfma_f32_16x16x32_bf16 v[72:75], v[176:179], v[200:203], v[72:75]
	v_mfma_f32_16x16x32_bf16 v[68:71], v[168:171], v[208:211], v[68:71]
	v_mfma_f32_16x16x32_bf16 v[64:67], v[176:179], v[208:211], v[64:67]
	v_mfma_f32_16x16x32_bf16 v[112:115], v[172:175], v[188:191], v[112:115]
	v_mfma_f32_16x16x32_bf16 v[104:107], v[180:183], v[188:191], v[104:107]
	v_mfma_f32_16x16x32_bf16 v[96:99], v[172:175], v[196:199], v[96:99]
	v_mfma_f32_16x16x32_bf16 v[88:91], v[180:183], v[196:199], v[88:91]
	v_mfma_f32_16x16x32_bf16 v[80:83], v[172:175], v[204:207], v[80:83]
	v_mfma_f32_16x16x32_bf16 v[72:75], v[180:183], v[204:207], v[72:75]
	v_mfma_f32_16x16x32_bf16 v[68:71], v[172:175], v[212:215], v[68:71]
	v_mfma_f32_16x16x32_bf16 v[64:67], v[180:183], v[212:215], v[64:67]
	s_barrier
	s_add_i32 s37, s37, s53
	s_mov_b32 m0, s37
	ds_read_b128 v[184:187], v151 offset:49152
	ds_read_b128 v[188:191], v151 offset:50176
	ds_read_b128 v[192:195], v151 offset:51200
	ds_read_b128 v[196:199], v151 offset:52224
	ds_read_b128 v[200:203], v151 offset:53248
	ds_read_b128 v[204:207], v151 offset:54272
	ds_read_b128 v[208:211], v151 offset:55296
	ds_read_b128 v[212:215], v151 offset:56320
	s_add_u32 s100, s48, 0x80
	s_addc_u32 s101, s49, 0
	global_load_lds_dwordx4 v130, s[100:101]
	s_add_i32 m0, s37, 0x2000
	s_add_u32 s38, s48, 0x20080
	s_addc_u32 s39, s49, 0
	s_add_i32 s37, s40, s53
	s_add_u32 s100, s48, 0x80
	s_addc_u32 s101, s49, 0
	global_load_lds_dwordx4 v134, s[100:101]
	s_mov_b32 m0, s37
	s_nop 0
	global_load_lds_dwordx4 v130, s[38:39]
	s_add_i32 m0, s37, 0x2000
	s_nop 0
	global_load_lds_dwordx4 v134, s[38:39]
	s_mov_b32 m0, s58
	s_nop 0
	s_add_u32 s100, s50, 0x80
	s_addc_u32 s101, s51, 0
	global_load_lds_dwordx4 v128, s[100:101]
	s_mov_b32 m0, s59
	s_nop 0
	s_add_u32 s100, s50, 0x80
	s_addc_u32 s101, s51, 0
	global_load_lds_dwordx4 v132, s[100:101]
	s_add_i32 s36, s36, 2
	s_add_u32 s46, s46, 0x100
	s_addc_u32 s47, s47, 0
	s_add_u32 s34, s34, 0x100
	s_addc_u32 s35, s35, 0
	s_cmp_gt_u32 s36, 29
	s_waitcnt vmcnt(8)
	s_waitcnt lgkmcnt(0)
	s_barrier
	s_waitcnt lgkmcnt(0)
	v_mfma_f32_16x16x32_bf16 v[60:63], v[152:155], v[184:187], v[60:63]
	v_mfma_f32_16x16x32_bf16 v[56:59], v[160:163], v[184:187], v[56:59]
	v_mfma_f32_16x16x32_bf16 v[52:55], v[152:155], v[192:195], v[52:55]
	v_mfma_f32_16x16x32_bf16 v[44:47], v[160:163], v[192:195], v[44:47]
	v_mfma_f32_16x16x32_bf16 v[36:39], v[152:155], v[200:203], v[36:39]
	v_mfma_f32_16x16x32_bf16 v[28:31], v[160:163], v[200:203], v[28:31]
	v_mfma_f32_16x16x32_bf16 v[20:23], v[152:155], v[208:211], v[20:23]
	v_mfma_f32_16x16x32_bf16 v[12:15], v[160:163], v[208:211], v[12:15]
	v_mfma_f32_16x16x32_bf16 v[60:63], v[156:159], v[188:191], v[60:63]
	v_mfma_f32_16x16x32_bf16 v[56:59], v[164:167], v[188:191], v[56:59]
	v_mfma_f32_16x16x32_bf16 v[52:55], v[156:159], v[196:199], v[52:55]
	v_mfma_f32_16x16x32_bf16 v[44:47], v[164:167], v[196:199], v[44:47]
	v_mfma_f32_16x16x32_bf16 v[36:39], v[156:159], v[204:207], v[36:39]
	v_mfma_f32_16x16x32_bf16 v[28:31], v[164:167], v[204:207], v[28:31]
	v_mfma_f32_16x16x32_bf16 v[20:23], v[156:159], v[212:215], v[20:23]
	v_mfma_f32_16x16x32_bf16 v[12:15], v[164:167], v[212:215], v[12:15]
	v_mfma_f32_16x16x32_bf16 v[48:51], v[168:171], v[184:187], v[48:51]
	v_mfma_f32_16x16x32_bf16 v[40:43], v[176:179], v[184:187], v[40:43]
	v_mfma_f32_16x16x32_bf16 v[32:35], v[168:171], v[192:195], v[32:35]
	v_mfma_f32_16x16x32_bf16 v[24:27], v[176:179], v[192:195], v[24:27]
	v_mfma_f32_16x16x32_bf16 v[16:19], v[168:171], v[200:203], v[16:19]
	v_mfma_f32_16x16x32_bf16 v[8:11], v[176:179], v[200:203], v[8:11]
	v_mfma_f32_16x16x32_bf16 v[4:7], v[168:171], v[208:211], v[4:7]
	v_mfma_f32_16x16x32_bf16 v[0:3], v[176:179], v[208:211], v[0:3]
	v_mfma_f32_16x16x32_bf16 v[48:51], v[172:175], v[188:191], v[48:51]
	v_mfma_f32_16x16x32_bf16 v[40:43], v[180:183], v[188:191], v[40:43]
	v_mfma_f32_16x16x32_bf16 v[32:35], v[172:175], v[196:199], v[32:35]
	v_mfma_f32_16x16x32_bf16 v[24:27], v[180:183], v[196:199], v[24:27]
	v_mfma_f32_16x16x32_bf16 v[16:19], v[172:175], v[204:207], v[16:19]
	v_mfma_f32_16x16x32_bf16 v[8:11], v[180:183], v[204:207], v[8:11]
	v_mfma_f32_16x16x32_bf16 v[4:7], v[172:175], v[212:215], v[4:7]
	v_mfma_f32_16x16x32_bf16 v[0:3], v[180:183], v[212:215], v[0:3]
	s_barrier
	s_cbranch_scc0 .LBB0_521
	s_setprio 0
	s_and_b64 vcc, exec, s[8:9]
	s_cbranch_vccz .LBB0_524
	s_barrier

.Lmy_prio_skip2:
.LBB0_600:
	ds_read_b128 v[152:155], v149
	ds_read_b128 v[156:159], v149 offset:1024
	ds_read_b128 v[160:163], v149 offset:2048
	ds_read_b128 v[164:167], v149 offset:3072
	ds_read_b128 v[168:171], v150
	ds_read_b128 v[172:175], v150 offset:1024
	ds_read_b128 v[176:179], v150 offset:2048
	ds_read_b128 v[180:183], v150 offset:3072
	s_add_u32 s37, s48, 0xfff00080
	s_addc_u32 s38, s49, -1
	s_cmp_eq_u32 s36, 60
	s_cselect_b32 s53, s17, s38
	s_cselect_b32 s52, s66, s37
	s_cselect_b32 s51, s13, s35
	s_cselect_b32 s50, s67, s34
	s_add_i32 m0, s19, 0xc000
	ds_read_b128 v[184:187], v151
	ds_read_b128 v[188:191], v151 offset:1024
	ds_read_b128 v[192:195], v151 offset:2048
	ds_read_b128 v[196:199], v151 offset:3072
	ds_read_b128 v[200:203], v151 offset:4096
	ds_read_b128 v[204:207], v151 offset:5120
	ds_read_b128 v[208:211], v151 offset:6144
	ds_read_b128 v[212:215], v151 offset:7168
	global_load_lds_dwordx4 v136, s[48:49]
	s_add_i32 m0, s19, 0xe000
	s_nop 0
	global_load_lds_dwordx4 v138, s[48:49]
	s_waitcnt vmcnt(8)
	s_waitcnt lgkmcnt(0)
	s_barrier
	s_waitcnt lgkmcnt(0)
	v_mfma_f32_16x16x32_bf16 v[124:127], v[152:155], v[184:187], v[124:127]
	v_mfma_f32_16x16x32_bf16 v[120:123], v[160:163], v[184:187], v[120:123]
	v_mfma_f32_16x16x32_bf16 v[116:119], v[152:155], v[192:195], v[116:119]
	v_mfma_f32_16x16x32_bf16 v[108:111], v[160:163], v[192:195], v[108:111]
	v_mfma_f32_16x16x32_bf16 v[100:103], v[152:155], v[200:203], v[100:103]
	v_mfma_f32_16x16x32_bf16 v[92:95], v[160:163], v[200:203], v[92:95]
	v_mfma_f32_16x16x32_bf16 v[84:87], v[152:155], v[208:211], v[84:87]
	v_mfma_f32_16x16x32_bf16 v[76:79], v[160:163], v[208:211], v[76:79]
	v_mfma_f32_16x16x32_bf16 v[124:127], v[156:159], v[188:191], v[124:127]
	v_mfma_f32_16x16x32_bf16 v[120:123], v[164:167], v[188:191], v[120:123]
	v_mfma_f32_16x16x32_bf16 v[116:119], v[156:159], v[196:199], v[116:119]
	v_mfma_f32_16x16x32_bf16 v[108:111], v[164:167], v[196:199], v[108:111]
	v_mfma_f32_16x16x32_bf16 v[100:103], v[156:159], v[204:207], v[100:103]
	v_mfma_f32_16x16x32_bf16 v[92:95], v[164:167], v[204:207], v[92:95]
	v_mfma_f32_16x16x32_bf16 v[84:87], v[156:159], v[212:215], v[84:87]
	v_mfma_f32_16x16x32_bf16 v[76:79], v[164:167], v[212:215], v[76:79]
	v_mfma_f32_16x16x32_bf16 v[112:115], v[168:171], v[184:187], v[112:115]
	v_mfma_f32_16x16x32_bf16 v[104:107], v[176:179], v[184:187], v[104:107]
	v_mfma_f32_16x16x32_bf16 v[96:99], v[168:171], v[192:195], v[96:99]
	v_mfma_f32_16x16x32_bf16 v[88:91], v[176:179], v[192:195], v[88:91]
	v_mfma_f32_16x16x32_bf16 v[80:83], v[168:171], v[200:203], v[80:83]
	v_mfma_f32_16x16x32_bf16 v[72:75], v[176:179], v[200:203], v[72:75]
	v_mfma_f32_16x16x32_bf16 v[68:71], v[168:171], v[208:211], v[68:71]
	v_mfma_f32_16x16x32_bf16 v[64:67], v[176:179], v[208:211], v[64:67]
	v_mfma_f32_16x16x32_bf16 v[112:115], v[172:175], v[188:191], v[112:115]
	v_mfma_f32_16x16x32_bf16 v[104:107], v[180:183], v[188:191], v[104:107]
	v_mfma_f32_16x16x32_bf16 v[96:99], v[172:175], v[196:199], v[96:99]
	v_mfma_f32_16x16x32_bf16 v[88:91], v[180:183], v[196:199], v[88:91]
	v_mfma_f32_16x16x32_bf16 v[80:83], v[172:175], v[204:207], v[80:83]
	v_mfma_f32_16x16x32_bf16 v[72:75], v[180:183], v[204:207], v[72:75]
	v_mfma_f32_16x16x32_bf16 v[68:71], v[172:175], v[212:215], v[68:71]
	v_mfma_f32_16x16x32_bf16 v[64:67], v[180:183], v[212:215], v[64:67]
	s_barrier
	s_add_i32 s37, s63, s55
	s_mov_b32 m0, s37
	ds_read_b128 v[184:187], v151 offset:16384
	ds_read_b128 v[188:191], v151 offset:17408
	ds_read_b128 v[192:195], v151 offset:18432
	ds_read_b128 v[196:199], v151 offset:19456
	ds_read_b128 v[200:203], v151 offset:20480
	ds_read_b128 v[204:207], v151 offset:21504
	ds_read_b128 v[208:211], v151 offset:22528
	ds_read_b128 v[212:215], v151 offset:23552
	global_load_lds_dwordx4 v130, s[50:51]
	s_add_i32 m0, s37, 0x2000
	s_add_u32 s38, s50, 0x40000
	s_addc_u32 s39, s51, 0
	s_add_i32 s37, s64, s55
	global_load_lds_dwordx4 v134, s[50:51]
	s_mov_b32 m0, s37
	global_load_lds_dwordx4 v130, s[38:39]
	s_add_i32 m0, s37, 0x2000
	s_nop 0
	global_load_lds_dwordx4 v134, s[38:39]
	s_mov_b32 m0, s19
	s_nop 0
	global_load_lds_dwordx4 v128, s[52:53]
	s_mov_b32 m0, s56
	s_nop 0
	global_load_lds_dwordx4 v132, s[52:53]
	s_waitcnt vmcnt(8)
	s_waitcnt lgkmcnt(0)
	s_barrier
	s_waitcnt lgkmcnt(0)
	v_mfma_f32_16x16x32_bf16 v[60:63], v[152:155], v[184:187], v[60:63]
	v_mfma_f32_16x16x32_bf16 v[56:59], v[160:163], v[184:187], v[56:59]
	v_mfma_f32_16x16x32_bf16 v[52:55], v[152:155], v[192:195], v[52:55]
	v_mfma_f32_16x16x32_bf16 v[44:47], v[160:163], v[192:195], v[44:47]
	v_mfma_f32_16x16x32_bf16 v[36:39], v[152:155], v[200:203], v[36:39]
	v_mfma_f32_16x16x32_bf16 v[28:31], v[160:163], v[200:203], v[28:31]
	v_mfma_f32_16x16x32_bf16 v[20:23], v[152:155], v[208:211], v[20:23]
	v_mfma_f32_16x16x32_bf16 v[12:15], v[160:163], v[208:211], v[12:15]
	v_mfma_f32_16x16x32_bf16 v[60:63], v[156:159], v[188:191], v[60:63]
	v_mfma_f32_16x16x32_bf16 v[56:59], v[164:167], v[188:191], v[56:59]
	v_mfma_f32_16x16x32_bf16 v[52:55], v[156:159], v[196:199], v[52:55]
	v_mfma_f32_16x16x32_bf16 v[44:47], v[164:167], v[196:199], v[44:47]
	v_mfma_f32_16x16x32_bf16 v[36:39], v[156:159], v[204:207], v[36:39]
	v_mfma_f32_16x16x32_bf16 v[28:31], v[164:167], v[204:207], v[28:31]
	v_mfma_f32_16x16x32_bf16 v[20:23], v[156:159], v[212:215], v[20:23]
	v_mfma_f32_16x16x32_bf16 v[12:15], v[164:167], v[212:215], v[12:15]
	v_mfma_f32_16x16x32_bf16 v[48:51], v[168:171], v[184:187], v[48:51]
	v_mfma_f32_16x16x32_bf16 v[40:43], v[176:179], v[184:187], v[40:43]
	v_mfma_f32_16x16x32_bf16 v[32:35], v[168:171], v[192:195], v[32:35]
	v_mfma_f32_16x16x32_bf16 v[24:27], v[176:179], v[192:195], v[24:27]
	v_mfma_f32_16x16x32_bf16 v[16:19], v[168:171], v[200:203], v[16:19]
	v_mfma_f32_16x16x32_bf16 v[8:11], v[176:179], v[200:203], v[8:11]
	v_mfma_f32_16x16x32_bf16 v[4:7], v[168:171], v[208:211], v[4:7]
	v_mfma_f32_16x16x32_bf16 v[0:3], v[176:179], v[208:211], v[0:3]
	v_mfma_f32_16x16x32_bf16 v[48:51], v[172:175], v[188:191], v[48:51]
	v_mfma_f32_16x16x32_bf16 v[40:43], v[180:183], v[188:191], v[40:43]
	v_mfma_f32_16x16x32_bf16 v[32:35], v[172:175], v[196:199], v[32:35]
	v_mfma_f32_16x16x32_bf16 v[24:27], v[180:183], v[196:199], v[24:27]
	v_mfma_f32_16x16x32_bf16 v[16:19], v[172:175], v[204:207], v[16:19]
	v_mfma_f32_16x16x32_bf16 v[8:11], v[180:183], v[204:207], v[8:11]
	v_mfma_f32_16x16x32_bf16 v[4:7], v[172:175], v[212:215], v[4:7]
	v_mfma_f32_16x16x32_bf16 v[0:3], v[180:183], v[212:215], v[0:3]
	s_barrier
	s_add_i32 s37, 0, 0x18000
	s_add_i32 s40, 0, 0x1c000
	v_add_u32_e32 v164, s37, v147
	v_add_u32_e32 v180, s40, v147
	ds_read_b128 v[152:155], v164
	ds_read_b128 v[156:159], v164 offset:1024
	ds_read_b128 v[160:163], v164 offset:2048
	ds_read_b128 v[164:167], v164 offset:3072
	ds_read_b128 v[168:171], v180
	ds_read_b128 v[172:175], v180 offset:1024
	ds_read_b128 v[176:179], v180 offset:2048
	ds_read_b128 v[180:183], v180 offset:3072
	s_add_u32 s38, s52, 0x100000
	s_addc_u32 s39, s53, 0
	s_mov_b32 m0, s57
	ds_read_b128 v[184:187], v151 offset:32768
	ds_read_b128 v[188:191], v151 offset:33792
	ds_read_b128 v[192:195], v151 offset:34816
	ds_read_b128 v[196:199], v151 offset:35840
	ds_read_b128 v[200:203], v151 offset:36864
	ds_read_b128 v[204:207], v151 offset:37888
	ds_read_b128 v[208:211], v151 offset:38912
	ds_read_b128 v[212:215], v151 offset:39936
	global_load_lds_dwordx4 v128, s[38:39]
	s_mov_b32 m0, s58
	s_nop 0
	global_load_lds_dwordx4 v132, s[38:39]
	s_waitcnt vmcnt(8)
	s_waitcnt lgkmcnt(0)
	s_barrier
	s_waitcnt lgkmcnt(0)
	v_mfma_f32_16x16x32_bf16 v[124:127], v[152:155], v[184:187], v[124:127]
	v_mfma_f32_16x16x32_bf16 v[120:123], v[160:163], v[184:187], v[120:123]
	v_mfma_f32_16x16x32_bf16 v[116:119], v[152:155], v[192:195], v[116:119]
	v_mfma_f32_16x16x32_bf16 v[108:111], v[160:163], v[192:195], v[108:111]
	v_mfma_f32_16x16x32_bf16 v[100:103], v[152:155], v[200:203], v[100:103]
	v_mfma_f32_16x16x32_bf16 v[92:95], v[160:163], v[200:203], v[92:95]
	v_mfma_f32_16x16x32_bf16 v[84:87], v[152:155], v[208:211], v[84:87]
	v_mfma_f32_16x16x32_bf16 v[76:79], v[160:163], v[208:211], v[76:79]
	v_mfma_f32_16x16x32_bf16 v[124:127], v[156:159], v[188:191], v[124:127]
	v_mfma_f32_16x16x32_bf16 v[120:123], v[164:167], v[188:191], v[120:123]
	v_mfma_f32_16x16x32_bf16 v[116:119], v[156:159], v[196:199], v[116:119]
	v_mfma_f32_16x16x32_bf16 v[108:111], v[164:167], v[196:199], v[108:111]
	v_mfma_f32_16x16x32_bf16 v[100:103], v[156:159], v[204:207], v[100:103]
	v_mfma_f32_16x16x32_bf16 v[92:95], v[164:167], v[204:207], v[92:95]
	v_mfma_f32_16x16x32_bf16 v[84:87], v[156:159], v[212:215], v[84:87]
	v_mfma_f32_16x16x32_bf16 v[76:79], v[164:167], v[212:215], v[76:79]
	v_mfma_f32_16x16x32_bf16 v[112:115], v[168:171], v[184:187], v[112:115]
	v_mfma_f32_16x16x32_bf16 v[104:107], v[176:179], v[184:187], v[104:107]
	v_mfma_f32_16x16x32_bf16 v[96:99], v[168:171], v[192:195], v[96:99]
	v_mfma_f32_16x16x32_bf16 v[88:91], v[176:179], v[192:195], v[88:91]
	v_mfma_f32_16x16x32_bf16 v[80:83], v[168:171], v[200:203], v[80:83]
	v_mfma_f32_16x16x32_bf16 v[72:75], v[176:179], v[200:203], v[72:75]
	v_mfma_f32_16x16x32_bf16 v[68:71], v[168:171], v[208:211], v[68:71]
	v_mfma_f32_16x16x32_bf16 v[64:67], v[176:179], v[208:211], v[64:67]
	v_mfma_f32_16x16x32_bf16 v[112:115], v[172:175], v[188:191], v[112:115]
	v_mfma_f32_16x16x32_bf16 v[104:107], v[180:183], v[188:191], v[104:107]
	v_mfma_f32_16x16x32_bf16 v[96:99], v[172:175], v[196:199], v[96:99]
	v_mfma_f32_16x16x32_bf16 v[88:91], v[180:183], v[196:199], v[88:91]
	v_mfma_f32_16x16x32_bf16 v[80:83], v[172:175], v[204:207], v[80:83]
	v_mfma_f32_16x16x32_bf16 v[72:75], v[180:183], v[204:207], v[72:75]
	v_mfma_f32_16x16x32_bf16 v[68:71], v[172:175], v[212:215], v[68:71]
	v_mfma_f32_16x16x32_bf16 v[64:67], v[180:183], v[212:215], v[64:67]
	s_barrier
	s_add_i32 s37, s37, s55
	s_mov_b32 m0, s37
	ds_read_b128 v[184:187], v151 offset:49152
	ds_read_b128 v[188:191], v151 offset:50176
	ds_read_b128 v[192:195], v151 offset:51200
	ds_read_b128 v[196:199], v151 offset:52224
	ds_read_b128 v[200:203], v151 offset:53248
	ds_read_b128 v[204:207], v151 offset:54272
	ds_read_b128 v[208:211], v151 offset:55296
	ds_read_b128 v[212:215], v151 offset:56320
	s_add_u32 s100, s50, 0x80
	s_addc_u32 s101, s51, 0
	global_load_lds_dwordx4 v130, s[100:101]
	s_add_i32 m0, s37, 0x2000
	s_add_u32 s38, s50, 0x40080
	s_addc_u32 s39, s51, 0
	s_add_i32 s37, s40, s55
	s_add_u32 s100, s50, 0x80
	s_addc_u32 s101, s51, 0
	global_load_lds_dwordx4 v134, s[100:101]
	s_mov_b32 m0, s37
	s_nop 0
	global_load_lds_dwordx4 v130, s[38:39]
	s_add_i32 m0, s37, 0x2000
	s_nop 0
	global_load_lds_dwordx4 v134, s[38:39]
	s_mov_b32 m0, s60
	s_nop 0
	s_add_u32 s100, s52, 0x80
	s_addc_u32 s101, s53, 0
	global_load_lds_dwordx4 v128, s[100:101]
	s_mov_b32 m0, s61
	s_nop 0
	s_add_u32 s100, s52, 0x80
	s_addc_u32 s101, s53, 0
	global_load_lds_dwordx4 v132, s[100:101]
	s_add_i32 s36, s36, 2
	s_add_u32 s48, s48, 0x100
	s_addc_u32 s49, s49, 0
	s_add_u32 s34, s34, 0x100
	s_addc_u32 s35, s35, 0
	s_cmp_gt_u32 s36, 61
	s_waitcnt vmcnt(8)
	s_waitcnt lgkmcnt(0)
	s_barrier
	s_waitcnt lgkmcnt(0)
	v_mfma_f32_16x16x32_bf16 v[60:63], v[152:155], v[184:187], v[60:63]
	v_mfma_f32_16x16x32_bf16 v[56:59], v[160:163], v[184:187], v[56:59]
	v_mfma_f32_16x16x32_bf16 v[52:55], v[152:155], v[192:195], v[52:55]
	v_mfma_f32_16x16x32_bf16 v[44:47], v[160:163], v[192:195], v[44:47]
	v_mfma_f32_16x16x32_bf16 v[36:39], v[152:155], v[200:203], v[36:39]
	v_mfma_f32_16x16x32_bf16 v[28:31], v[160:163], v[200:203], v[28:31]
	v_mfma_f32_16x16x32_bf16 v[20:23], v[152:155], v[208:211], v[20:23]
	v_mfma_f32_16x16x32_bf16 v[12:15], v[160:163], v[208:211], v[12:15]
	v_mfma_f32_16x16x32_bf16 v[60:63], v[156:159], v[188:191], v[60:63]
	v_mfma_f32_16x16x32_bf16 v[56:59], v[164:167], v[188:191], v[56:59]
	v_mfma_f32_16x16x32_bf16 v[52:55], v[156:159], v[196:199], v[52:55]
	v_mfma_f32_16x16x32_bf16 v[44:47], v[164:167], v[196:199], v[44:47]
	v_mfma_f32_16x16x32_bf16 v[36:39], v[156:159], v[204:207], v[36:39]
	v_mfma_f32_16x16x32_bf16 v[28:31], v[164:167], v[204:207], v[28:31]
	v_mfma_f32_16x16x32_bf16 v[20:23], v[156:159], v[212:215], v[20:23]
	v_mfma_f32_16x16x32_bf16 v[12:15], v[164:167], v[212:215], v[12:15]
	v_mfma_f32_16x16x32_bf16 v[48:51], v[168:171], v[184:187], v[48:51]
	v_mfma_f32_16x16x32_bf16 v[40:43], v[176:179], v[184:187], v[40:43]
	v_mfma_f32_16x16x32_bf16 v[32:35], v[168:171], v[192:195], v[32:35]
	v_mfma_f32_16x16x32_bf16 v[24:27], v[176:179], v[192:195], v[24:27]
	v_mfma_f32_16x16x32_bf16 v[16:19], v[168:171], v[200:203], v[16:19]
	v_mfma_f32_16x16x32_bf16 v[8:11], v[176:179], v[200:203], v[8:11]
	v_mfma_f32_16x16x32_bf16 v[4:7], v[168:171], v[208:211], v[4:7]
	v_mfma_f32_16x16x32_bf16 v[0:3], v[176:179], v[208:211], v[0:3]
	v_mfma_f32_16x16x32_bf16 v[48:51], v[172:175], v[188:191], v[48:51]
	v_mfma_f32_16x16x32_bf16 v[40:43], v[180:183], v[188:191], v[40:43]
	v_mfma_f32_16x16x32_bf16 v[32:35], v[172:175], v[196:199], v[32:35]
	v_mfma_f32_16x16x32_bf16 v[24:27], v[180:183], v[196:199], v[24:27]
	v_mfma_f32_16x16x32_bf16 v[16:19], v[172:175], v[204:207], v[16:19]
	v_mfma_f32_16x16x32_bf16 v[8:11], v[180:183], v[204:207], v[8:11]
	v_mfma_f32_16x16x32_bf16 v[4:7], v[172:175], v[212:215], v[4:7]
	v_mfma_f32_16x16x32_bf16 v[0:3], v[180:183], v[212:215], v[0:3]
	s_barrier
	s_cbranch_scc0 .LBB0_600
	s_setprio 0
	s_and_b64 vcc, exec, s[10:11]
	s_cbranch_vccz .LBB0_603
	s_barrier

.Lmy_prio_skip3:
.LBB0_679:
	ds_read_b128 v[144:147], v151
	ds_read_b128 v[154:157], v151 offset:1024
	ds_read_b128 v[158:161], v151 offset:2048
	ds_read_b128 v[162:165], v151 offset:3072
	ds_read_b128 v[166:169], v152
	ds_read_b128 v[170:173], v152 offset:1024
	ds_read_b128 v[174:177], v152 offset:2048
	ds_read_b128 v[178:181], v152 offset:3072
	s_add_u32 s37, s50, 0xfff00080
	s_addc_u32 s38, s51, -1
	s_cmp_eq_u32 s36, 60
	s_cselect_b32 s55, s19, s38
	s_cselect_b32 s54, s66, s37
	s_cselect_b32 s53, s17, s35
	s_cselect_b32 s52, s67, s34
	s_add_i32 m0, s49, 0xc000
	ds_read_b128 v[182:185], v153
	ds_read_b128 v[186:189], v153 offset:1024
	ds_read_b128 v[190:193], v153 offset:2048
	ds_read_b128 v[194:197], v153 offset:3072
	ds_read_b128 v[198:201], v153 offset:4096
	ds_read_b128 v[202:205], v153 offset:5120
	ds_read_b128 v[206:209], v153 offset:6144
	ds_read_b128 v[210:213], v153 offset:7168
	global_load_lds_dwordx4 v136, s[50:51]
	s_add_i32 m0, s49, 0xe000
	s_nop 0
	global_load_lds_dwordx4 v138, s[50:51]
	s_waitcnt vmcnt(8)
	s_waitcnt lgkmcnt(0)
	s_barrier
	s_waitcnt lgkmcnt(0)
	v_mfma_f32_16x16x32_bf16 v[124:127], v[144:147], v[182:185], v[124:127]
	v_mfma_f32_16x16x32_bf16 v[116:119], v[158:161], v[182:185], v[116:119]
	v_mfma_f32_16x16x32_bf16 v[108:111], v[144:147], v[190:193], v[108:111]
	v_mfma_f32_16x16x32_bf16 v[104:107], v[158:161], v[190:193], v[104:107]
	v_mfma_f32_16x16x32_bf16 v[92:95], v[144:147], v[198:201], v[92:95]
	v_mfma_f32_16x16x32_bf16 v[88:91], v[158:161], v[198:201], v[88:91]
	v_mfma_f32_16x16x32_bf16 v[76:79], v[144:147], v[206:209], v[76:79]
	v_mfma_f32_16x16x32_bf16 v[72:75], v[158:161], v[206:209], v[72:75]
	v_mfma_f32_16x16x32_bf16 v[124:127], v[154:157], v[186:189], v[124:127]
	v_mfma_f32_16x16x32_bf16 v[116:119], v[162:165], v[186:189], v[116:119]
	v_mfma_f32_16x16x32_bf16 v[108:111], v[154:157], v[194:197], v[108:111]
	v_mfma_f32_16x16x32_bf16 v[104:107], v[162:165], v[194:197], v[104:107]
	v_mfma_f32_16x16x32_bf16 v[92:95], v[154:157], v[202:205], v[92:95]
	v_mfma_f32_16x16x32_bf16 v[88:91], v[162:165], v[202:205], v[88:91]
	v_mfma_f32_16x16x32_bf16 v[76:79], v[154:157], v[210:213], v[76:79]
	v_mfma_f32_16x16x32_bf16 v[72:75], v[162:165], v[210:213], v[72:75]
	v_mfma_f32_16x16x32_bf16 v[120:123], v[166:169], v[182:185], v[120:123]
	v_mfma_f32_16x16x32_bf16 v[112:115], v[174:177], v[182:185], v[112:115]
	v_mfma_f32_16x16x32_bf16 v[100:103], v[166:169], v[190:193], v[100:103]
	v_mfma_f32_16x16x32_bf16 v[96:99], v[174:177], v[190:193], v[96:99]
	v_mfma_f32_16x16x32_bf16 v[84:87], v[166:169], v[198:201], v[84:87]
	v_mfma_f32_16x16x32_bf16 v[80:83], v[174:177], v[198:201], v[80:83]
	v_mfma_f32_16x16x32_bf16 v[68:71], v[166:169], v[206:209], v[68:71]
	v_mfma_f32_16x16x32_bf16 v[64:67], v[174:177], v[206:209], v[64:67]
	v_mfma_f32_16x16x32_bf16 v[120:123], v[170:173], v[186:189], v[120:123]
	v_mfma_f32_16x16x32_bf16 v[112:115], v[178:181], v[186:189], v[112:115]
	v_mfma_f32_16x16x32_bf16 v[100:103], v[170:173], v[194:197], v[100:103]
	v_mfma_f32_16x16x32_bf16 v[96:99], v[178:181], v[194:197], v[96:99]
	v_mfma_f32_16x16x32_bf16 v[84:87], v[170:173], v[202:205], v[84:87]
	v_mfma_f32_16x16x32_bf16 v[80:83], v[178:181], v[202:205], v[80:83]
	v_mfma_f32_16x16x32_bf16 v[68:71], v[170:173], v[210:213], v[68:71]
	v_mfma_f32_16x16x32_bf16 v[64:67], v[178:181], v[210:213], v[64:67]
	s_barrier
	s_add_i32 s37, s63, s33
	s_mov_b32 m0, s37
	ds_read_b128 v[182:185], v153 offset:16384
	ds_read_b128 v[186:189], v153 offset:17408
	ds_read_b128 v[190:193], v153 offset:18432
	ds_read_b128 v[194:197], v153 offset:19456
	ds_read_b128 v[198:201], v153 offset:20480
	ds_read_b128 v[202:205], v153 offset:21504
	ds_read_b128 v[206:209], v153 offset:22528
	ds_read_b128 v[210:213], v153 offset:23552
	global_load_lds_dwordx4 v130, s[52:53]
	s_add_i32 m0, s37, 0x2000
	s_add_u32 s38, s52, 0x100000
	s_addc_u32 s39, s53, 0
	s_add_i32 s37, s64, s33
	global_load_lds_dwordx4 v134, s[52:53]
	s_mov_b32 m0, s37
	global_load_lds_dwordx4 v130, s[38:39]
	s_add_i32 m0, s37, 0x2000
	s_nop 0
	global_load_lds_dwordx4 v134, s[38:39]
	s_mov_b32 m0, s49
	s_nop 0
	global_load_lds_dwordx4 v128, s[54:55]
	s_mov_b32 m0, s56
	s_nop 0
	global_load_lds_dwordx4 v132, s[54:55]
	s_waitcnt vmcnt(8)
	s_waitcnt lgkmcnt(0)
	s_barrier
	s_waitcnt lgkmcnt(0)
	v_mfma_f32_16x16x32_bf16 v[60:63], v[144:147], v[182:185], v[60:63]
	v_mfma_f32_16x16x32_bf16 v[56:59], v[158:161], v[182:185], v[56:59]
	v_mfma_f32_16x16x32_bf16 v[44:47], v[144:147], v[190:193], v[44:47]
	v_mfma_f32_16x16x32_bf16 v[40:43], v[158:161], v[190:193], v[40:43]
	v_mfma_f32_16x16x32_bf16 v[28:31], v[144:147], v[198:201], v[28:31]
	v_mfma_f32_16x16x32_bf16 v[24:27], v[158:161], v[198:201], v[24:27]
	v_mfma_f32_16x16x32_bf16 v[12:15], v[144:147], v[206:209], v[12:15]
	v_mfma_f32_16x16x32_bf16 v[8:11], v[158:161], v[206:209], v[8:11]
	v_mfma_f32_16x16x32_bf16 v[60:63], v[154:157], v[186:189], v[60:63]
	v_mfma_f32_16x16x32_bf16 v[56:59], v[162:165], v[186:189], v[56:59]
	v_mfma_f32_16x16x32_bf16 v[44:47], v[154:157], v[194:197], v[44:47]
	v_mfma_f32_16x16x32_bf16 v[40:43], v[162:165], v[194:197], v[40:43]
	v_mfma_f32_16x16x32_bf16 v[28:31], v[154:157], v[202:205], v[28:31]
	v_mfma_f32_16x16x32_bf16 v[24:27], v[162:165], v[202:205], v[24:27]
	v_mfma_f32_16x16x32_bf16 v[12:15], v[154:157], v[210:213], v[12:15]
	v_mfma_f32_16x16x32_bf16 v[8:11], v[162:165], v[210:213], v[8:11]
	v_mfma_f32_16x16x32_bf16 v[52:55], v[166:169], v[182:185], v[52:55]
	v_mfma_f32_16x16x32_bf16 v[48:51], v[174:177], v[182:185], v[48:51]
	v_mfma_f32_16x16x32_bf16 v[36:39], v[166:169], v[190:193], v[36:39]
	v_mfma_f32_16x16x32_bf16 v[32:35], v[174:177], v[190:193], v[32:35]
	v_mfma_f32_16x16x32_bf16 v[20:23], v[166:169], v[198:201], v[20:23]
	v_mfma_f32_16x16x32_bf16 v[16:19], v[174:177], v[198:201], v[16:19]
	v_mfma_f32_16x16x32_bf16 v[4:7], v[166:169], v[206:209], v[4:7]
	v_mfma_f32_16x16x32_bf16 v[0:3], v[174:177], v[206:209], v[0:3]
	v_mfma_f32_16x16x32_bf16 v[52:55], v[170:173], v[186:189], v[52:55]
	v_mfma_f32_16x16x32_bf16 v[48:51], v[178:181], v[186:189], v[48:51]
	v_mfma_f32_16x16x32_bf16 v[36:39], v[170:173], v[194:197], v[36:39]
	v_mfma_f32_16x16x32_bf16 v[32:35], v[178:181], v[194:197], v[32:35]
	v_mfma_f32_16x16x32_bf16 v[20:23], v[170:173], v[202:205], v[20:23]
	v_mfma_f32_16x16x32_bf16 v[16:19], v[178:181], v[202:205], v[16:19]
	v_mfma_f32_16x16x32_bf16 v[4:7], v[170:173], v[210:213], v[4:7]
	v_mfma_f32_16x16x32_bf16 v[0:3], v[178:181], v[210:213], v[0:3]
	s_barrier
	s_add_i32 s37, 0, 0x18000
	s_add_i32 s40, 0, 0x1c000
	v_add_u32_e32 v162, s37, v149
	v_add_u32_e32 v178, s40, v149
	ds_read_b128 v[144:147], v162
	ds_read_b128 v[154:157], v162 offset:1024
	ds_read_b128 v[158:161], v162 offset:2048
	ds_read_b128 v[162:165], v162 offset:3072
	ds_read_b128 v[166:169], v178
	ds_read_b128 v[170:173], v178 offset:1024
	ds_read_b128 v[174:177], v178 offset:2048
	ds_read_b128 v[178:181], v178 offset:3072
	s_add_u32 s38, s54, 0x100000
	s_addc_u32 s39, s55, 0
	s_mov_b32 m0, s57
	ds_read_b128 v[182:185], v153 offset:32768
	ds_read_b128 v[186:189], v153 offset:33792
	ds_read_b128 v[190:193], v153 offset:34816
	ds_read_b128 v[194:197], v153 offset:35840
	ds_read_b128 v[198:201], v153 offset:36864
	ds_read_b128 v[202:205], v153 offset:37888
	ds_read_b128 v[206:209], v153 offset:38912
	ds_read_b128 v[210:213], v153 offset:39936
	global_load_lds_dwordx4 v128, s[38:39]
	s_mov_b32 m0, s58
	s_nop 0
	global_load_lds_dwordx4 v132, s[38:39]
	s_waitcnt vmcnt(8)
	s_waitcnt lgkmcnt(0)
	s_barrier
	s_waitcnt lgkmcnt(0)
	v_mfma_f32_16x16x32_bf16 v[124:127], v[144:147], v[182:185], v[124:127]
	v_mfma_f32_16x16x32_bf16 v[116:119], v[158:161], v[182:185], v[116:119]
	v_mfma_f32_16x16x32_bf16 v[108:111], v[144:147], v[190:193], v[108:111]
	v_mfma_f32_16x16x32_bf16 v[104:107], v[158:161], v[190:193], v[104:107]
	v_mfma_f32_16x16x32_bf16 v[92:95], v[144:147], v[198:201], v[92:95]
	v_mfma_f32_16x16x32_bf16 v[88:91], v[158:161], v[198:201], v[88:91]
	v_mfma_f32_16x16x32_bf16 v[76:79], v[144:147], v[206:209], v[76:79]
	v_mfma_f32_16x16x32_bf16 v[72:75], v[158:161], v[206:209], v[72:75]
	v_mfma_f32_16x16x32_bf16 v[124:127], v[154:157], v[186:189], v[124:127]
	v_mfma_f32_16x16x32_bf16 v[116:119], v[162:165], v[186:189], v[116:119]
	v_mfma_f32_16x16x32_bf16 v[108:111], v[154:157], v[194:197], v[108:111]
	v_mfma_f32_16x16x32_bf16 v[104:107], v[162:165], v[194:197], v[104:107]
	v_mfma_f32_16x16x32_bf16 v[92:95], v[154:157], v[202:205], v[92:95]
	v_mfma_f32_16x16x32_bf16 v[88:91], v[162:165], v[202:205], v[88:91]
	v_mfma_f32_16x16x32_bf16 v[76:79], v[154:157], v[210:213], v[76:79]
	v_mfma_f32_16x16x32_bf16 v[72:75], v[162:165], v[210:213], v[72:75]
	v_mfma_f32_16x16x32_bf16 v[120:123], v[166:169], v[182:185], v[120:123]
	v_mfma_f32_16x16x32_bf16 v[112:115], v[174:177], v[182:185], v[112:115]
	v_mfma_f32_16x16x32_bf16 v[100:103], v[166:169], v[190:193], v[100:103]
	v_mfma_f32_16x16x32_bf16 v[96:99], v[174:177], v[190:193], v[96:99]
	v_mfma_f32_16x16x32_bf16 v[84:87], v[166:169], v[198:201], v[84:87]
	v_mfma_f32_16x16x32_bf16 v[80:83], v[174:177], v[198:201], v[80:83]
	v_mfma_f32_16x16x32_bf16 v[68:71], v[166:169], v[206:209], v[68:71]
	v_mfma_f32_16x16x32_bf16 v[64:67], v[174:177], v[206:209], v[64:67]
	v_mfma_f32_16x16x32_bf16 v[120:123], v[170:173], v[186:189], v[120:123]
	v_mfma_f32_16x16x32_bf16 v[112:115], v[178:181], v[186:189], v[112:115]
	v_mfma_f32_16x16x32_bf16 v[100:103], v[170:173], v[194:197], v[100:103]
	v_mfma_f32_16x16x32_bf16 v[96:99], v[178:181], v[194:197], v[96:99]
	v_mfma_f32_16x16x32_bf16 v[84:87], v[170:173], v[202:205], v[84:87]
	v_mfma_f32_16x16x32_bf16 v[80:83], v[178:181], v[202:205], v[80:83]
	v_mfma_f32_16x16x32_bf16 v[68:71], v[170:173], v[210:213], v[68:71]
	v_mfma_f32_16x16x32_bf16 v[64:67], v[178:181], v[210:213], v[64:67]
	s_barrier
	s_add_i32 s37, s37, s33
	s_mov_b32 m0, s37
	ds_read_b128 v[182:185], v153 offset:49152
	ds_read_b128 v[186:189], v153 offset:50176
	ds_read_b128 v[190:193], v153 offset:51200
	ds_read_b128 v[194:197], v153 offset:52224
	ds_read_b128 v[198:201], v153 offset:53248
	ds_read_b128 v[202:205], v153 offset:54272
	ds_read_b128 v[206:209], v153 offset:55296
	ds_read_b128 v[210:213], v153 offset:56320
	s_add_u32 s100, s52, 0x80
	s_addc_u32 s101, s53, 0
	global_load_lds_dwordx4 v130, s[100:101]
	s_add_i32 m0, s37, 0x2000
	s_add_u32 s38, s52, 0x100080
	s_addc_u32 s39, s53, 0
	s_add_i32 s37, s40, s33
	s_add_u32 s100, s52, 0x80
	s_addc_u32 s101, s53, 0
	global_load_lds_dwordx4 v134, s[100:101]
	s_mov_b32 m0, s37
	s_nop 0
	global_load_lds_dwordx4 v130, s[38:39]
	s_add_i32 m0, s37, 0x2000
	s_nop 0
	global_load_lds_dwordx4 v134, s[38:39]
	s_mov_b32 m0, s60
	s_nop 0
	s_add_u32 s100, s54, 0x80
	s_addc_u32 s101, s55, 0
	global_load_lds_dwordx4 v128, s[100:101]
	s_mov_b32 m0, s61
	s_nop 0
	s_add_u32 s100, s54, 0x80
	s_addc_u32 s101, s55, 0
	global_load_lds_dwordx4 v132, s[100:101]
	s_add_i32 s36, s36, 2
	s_add_u32 s50, s50, 0x100
	s_addc_u32 s51, s51, 0
	s_add_u32 s34, s34, 0x100
	s_addc_u32 s35, s35, 0
	s_cmp_gt_u32 s36, 61
	s_waitcnt vmcnt(8)
	s_waitcnt lgkmcnt(0)
	s_barrier
	s_waitcnt lgkmcnt(0)
	v_mfma_f32_16x16x32_bf16 v[60:63], v[144:147], v[182:185], v[60:63]
	v_mfma_f32_16x16x32_bf16 v[56:59], v[158:161], v[182:185], v[56:59]
	v_mfma_f32_16x16x32_bf16 v[44:47], v[144:147], v[190:193], v[44:47]
	v_mfma_f32_16x16x32_bf16 v[40:43], v[158:161], v[190:193], v[40:43]
	v_mfma_f32_16x16x32_bf16 v[28:31], v[144:147], v[198:201], v[28:31]
	v_mfma_f32_16x16x32_bf16 v[24:27], v[158:161], v[198:201], v[24:27]
	v_mfma_f32_16x16x32_bf16 v[12:15], v[144:147], v[206:209], v[12:15]
	v_mfma_f32_16x16x32_bf16 v[8:11], v[158:161], v[206:209], v[8:11]
	v_mfma_f32_16x16x32_bf16 v[60:63], v[154:157], v[186:189], v[60:63]
	v_mfma_f32_16x16x32_bf16 v[56:59], v[162:165], v[186:189], v[56:59]
	v_mfma_f32_16x16x32_bf16 v[44:47], v[154:157], v[194:197], v[44:47]
	v_mfma_f32_16x16x32_bf16 v[40:43], v[162:165], v[194:197], v[40:43]
	v_mfma_f32_16x16x32_bf16 v[28:31], v[154:157], v[202:205], v[28:31]
	v_mfma_f32_16x16x32_bf16 v[24:27], v[162:165], v[202:205], v[24:27]
	v_mfma_f32_16x16x32_bf16 v[12:15], v[154:157], v[210:213], v[12:15]
	v_mfma_f32_16x16x32_bf16 v[8:11], v[162:165], v[210:213], v[8:11]
	v_mfma_f32_16x16x32_bf16 v[52:55], v[166:169], v[182:185], v[52:55]
	v_mfma_f32_16x16x32_bf16 v[48:51], v[174:177], v[182:185], v[48:51]
	v_mfma_f32_16x16x32_bf16 v[36:39], v[166:169], v[190:193], v[36:39]
	v_mfma_f32_16x16x32_bf16 v[32:35], v[174:177], v[190:193], v[32:35]
	v_mfma_f32_16x16x32_bf16 v[20:23], v[166:169], v[198:201], v[20:23]
	v_mfma_f32_16x16x32_bf16 v[16:19], v[174:177], v[198:201], v[16:19]
	v_mfma_f32_16x16x32_bf16 v[4:7], v[166:169], v[206:209], v[4:7]
	v_mfma_f32_16x16x32_bf16 v[0:3], v[174:177], v[206:209], v[0:3]
	v_mfma_f32_16x16x32_bf16 v[52:55], v[170:173], v[186:189], v[52:55]
	v_mfma_f32_16x16x32_bf16 v[48:51], v[178:181], v[186:189], v[48:51]
	v_mfma_f32_16x16x32_bf16 v[36:39], v[170:173], v[194:197], v[36:39]
	v_mfma_f32_16x16x32_bf16 v[32:35], v[178:181], v[194:197], v[32:35]
	v_mfma_f32_16x16x32_bf16 v[20:23], v[170:173], v[202:205], v[20:23]
	v_mfma_f32_16x16x32_bf16 v[16:19], v[178:181], v[202:205], v[16:19]
	v_mfma_f32_16x16x32_bf16 v[4:7], v[170:173], v[210:213], v[4:7]
	v_mfma_f32_16x16x32_bf16 v[0:3], v[178:181], v[210:213], v[0:3]
	s_barrier
	s_cbranch_scc0 .LBB0_679
	s_setprio 0
	s_and_b64 vcc, exec, s[12:13]
	s_cbranch_vccz .LBB0_682
	s_barrier

.Lmy_prio_skip4:
.LBB0_758:
	ds_read_b128 v[144:147], v153
	ds_read_b128 v[156:159], v153 offset:1024
	ds_read_b128 v[160:163], v153 offset:2048
	ds_read_b128 v[164:167], v153 offset:3072
	ds_read_b128 v[168:171], v154
	ds_read_b128 v[172:175], v154 offset:1024
	ds_read_b128 v[176:179], v154 offset:2048
	ds_read_b128 v[180:183], v154 offset:3072
	s_add_u32 s37, s38, 0xfff00080
	s_addc_u32 s40, s39, -1
	s_cmp_eq_u32 s36, 60
	s_cselect_b32 s49, s13, s40
	s_cselect_b32 s48, s64, s37
	s_cselect_b32 s47, s11, s35
	s_cselect_b32 s46, s65, s34
	s_add_i32 m0, s76, 0xc000
	ds_read_b128 v[184:187], v155
	ds_read_b128 v[188:191], v155 offset:1024
	ds_read_b128 v[192:195], v155 offset:2048
	ds_read_b128 v[196:199], v155 offset:3072
	ds_read_b128 v[200:203], v155 offset:4096
	ds_read_b128 v[204:207], v155 offset:5120
	ds_read_b128 v[208:211], v155 offset:6144
	ds_read_b128 v[212:215], v155 offset:7168
	global_load_lds_dwordx4 v136, s[38:39]
	s_add_i32 m0, s76, 0xe000
	s_nop 0
	global_load_lds_dwordx4 v138, s[38:39]
	s_waitcnt vmcnt(8)
	s_waitcnt lgkmcnt(0)
	s_barrier
	s_waitcnt lgkmcnt(0)
	v_mfma_f32_16x16x32_bf16 v[124:127], v[144:147], v[184:187], v[124:127]
	v_mfma_f32_16x16x32_bf16 v[120:123], v[160:163], v[184:187], v[120:123]
	v_mfma_f32_16x16x32_bf16 v[108:111], v[144:147], v[192:195], v[108:111]
	v_mfma_f32_16x16x32_bf16 v[104:107], v[160:163], v[192:195], v[104:107]
	v_mfma_f32_16x16x32_bf16 v[92:95], v[144:147], v[200:203], v[92:95]
	v_mfma_f32_16x16x32_bf16 v[88:91], v[160:163], v[200:203], v[88:91]
	v_mfma_f32_16x16x32_bf16 v[76:79], v[144:147], v[208:211], v[76:79]
	v_mfma_f32_16x16x32_bf16 v[72:75], v[160:163], v[208:211], v[72:75]
	v_mfma_f32_16x16x32_bf16 v[124:127], v[156:159], v[188:191], v[124:127]
	v_mfma_f32_16x16x32_bf16 v[120:123], v[164:167], v[188:191], v[120:123]
	v_mfma_f32_16x16x32_bf16 v[108:111], v[156:159], v[196:199], v[108:111]
	v_mfma_f32_16x16x32_bf16 v[104:107], v[164:167], v[196:199], v[104:107]
	v_mfma_f32_16x16x32_bf16 v[92:95], v[156:159], v[204:207], v[92:95]
	v_mfma_f32_16x16x32_bf16 v[88:91], v[164:167], v[204:207], v[88:91]
	v_mfma_f32_16x16x32_bf16 v[76:79], v[156:159], v[212:215], v[76:79]
	v_mfma_f32_16x16x32_bf16 v[72:75], v[164:167], v[212:215], v[72:75]
	v_mfma_f32_16x16x32_bf16 v[116:119], v[168:171], v[184:187], v[116:119]
	v_mfma_f32_16x16x32_bf16 v[112:115], v[176:179], v[184:187], v[112:115]
	v_mfma_f32_16x16x32_bf16 v[100:103], v[168:171], v[192:195], v[100:103]
	v_mfma_f32_16x16x32_bf16 v[96:99], v[176:179], v[192:195], v[96:99]
	v_mfma_f32_16x16x32_bf16 v[84:87], v[168:171], v[200:203], v[84:87]
	v_mfma_f32_16x16x32_bf16 v[80:83], v[176:179], v[200:203], v[80:83]
	v_mfma_f32_16x16x32_bf16 v[68:71], v[168:171], v[208:211], v[68:71]
	v_mfma_f32_16x16x32_bf16 v[64:67], v[176:179], v[208:211], v[64:67]
	v_mfma_f32_16x16x32_bf16 v[116:119], v[172:175], v[188:191], v[116:119]
	v_mfma_f32_16x16x32_bf16 v[112:115], v[180:183], v[188:191], v[112:115]
	v_mfma_f32_16x16x32_bf16 v[100:103], v[172:175], v[196:199], v[100:103]
	v_mfma_f32_16x16x32_bf16 v[96:99], v[180:183], v[196:199], v[96:99]
	v_mfma_f32_16x16x32_bf16 v[84:87], v[172:175], v[204:207], v[84:87]
	v_mfma_f32_16x16x32_bf16 v[80:83], v[180:183], v[204:207], v[80:83]
	v_mfma_f32_16x16x32_bf16 v[68:71], v[172:175], v[212:215], v[68:71]
	v_mfma_f32_16x16x32_bf16 v[64:67], v[180:183], v[212:215], v[64:67]
	s_barrier
	s_add_i32 s37, s61, s67
	s_mov_b32 m0, s37
	ds_read_b128 v[184:187], v155 offset:16384
	ds_read_b128 v[188:191], v155 offset:17408
	ds_read_b128 v[192:195], v155 offset:18432
	ds_read_b128 v[196:199], v155 offset:19456
	ds_read_b128 v[200:203], v155 offset:20480
	ds_read_b128 v[204:207], v155 offset:21504
	ds_read_b128 v[208:211], v155 offset:22528
	ds_read_b128 v[212:215], v155 offset:23552
	global_load_lds_dwordx4 v130, s[46:47]
	s_add_i32 m0, s37, 0x2000
	s_add_u32 s40, s46, 0x100000
	s_addc_u32 s41, s47, 0
	s_add_i32 s37, s62, s67
	global_load_lds_dwordx4 v134, s[46:47]
	s_mov_b32 m0, s37
	global_load_lds_dwordx4 v130, s[40:41]
	s_add_i32 m0, s37, 0x2000
	s_nop 0
	global_load_lds_dwordx4 v134, s[40:41]
	s_mov_b32 m0, s76
	s_nop 0
	global_load_lds_dwordx4 v128, s[48:49]
	s_mov_b32 m0, s52
	s_nop 0
	global_load_lds_dwordx4 v132, s[48:49]
	s_waitcnt vmcnt(8)
	s_waitcnt lgkmcnt(0)
	s_barrier
	s_waitcnt lgkmcnt(0)
	v_mfma_f32_16x16x32_bf16 v[60:63], v[144:147], v[184:187], v[60:63]
	v_mfma_f32_16x16x32_bf16 v[56:59], v[160:163], v[184:187], v[56:59]
	v_mfma_f32_16x16x32_bf16 v[44:47], v[144:147], v[192:195], v[44:47]
	v_mfma_f32_16x16x32_bf16 v[40:43], v[160:163], v[192:195], v[40:43]
	v_mfma_f32_16x16x32_bf16 v[28:31], v[144:147], v[200:203], v[28:31]
	v_mfma_f32_16x16x32_bf16 v[24:27], v[160:163], v[200:203], v[24:27]
	v_mfma_f32_16x16x32_bf16 v[12:15], v[144:147], v[208:211], v[12:15]
	v_mfma_f32_16x16x32_bf16 v[8:11], v[160:163], v[208:211], v[8:11]
	v_mfma_f32_16x16x32_bf16 v[60:63], v[156:159], v[188:191], v[60:63]
	v_mfma_f32_16x16x32_bf16 v[56:59], v[164:167], v[188:191], v[56:59]
	v_mfma_f32_16x16x32_bf16 v[44:47], v[156:159], v[196:199], v[44:47]
	v_mfma_f32_16x16x32_bf16 v[40:43], v[164:167], v[196:199], v[40:43]
	v_mfma_f32_16x16x32_bf16 v[28:31], v[156:159], v[204:207], v[28:31]
	v_mfma_f32_16x16x32_bf16 v[24:27], v[164:167], v[204:207], v[24:27]
	v_mfma_f32_16x16x32_bf16 v[12:15], v[156:159], v[212:215], v[12:15]
	v_mfma_f32_16x16x32_bf16 v[8:11], v[164:167], v[212:215], v[8:11]
	v_mfma_f32_16x16x32_bf16 v[52:55], v[168:171], v[184:187], v[52:55]
	v_mfma_f32_16x16x32_bf16 v[48:51], v[176:179], v[184:187], v[48:51]
	v_mfma_f32_16x16x32_bf16 v[36:39], v[168:171], v[192:195], v[36:39]
	v_mfma_f32_16x16x32_bf16 v[32:35], v[176:179], v[192:195], v[32:35]
	v_mfma_f32_16x16x32_bf16 v[20:23], v[168:171], v[200:203], v[20:23]
	v_mfma_f32_16x16x32_bf16 v[16:19], v[176:179], v[200:203], v[16:19]
	v_mfma_f32_16x16x32_bf16 v[4:7], v[168:171], v[208:211], v[4:7]
	v_mfma_f32_16x16x32_bf16 v[0:3], v[176:179], v[208:211], v[0:3]
	v_mfma_f32_16x16x32_bf16 v[52:55], v[172:175], v[188:191], v[52:55]
	v_mfma_f32_16x16x32_bf16 v[48:51], v[180:183], v[188:191], v[48:51]
	v_mfma_f32_16x16x32_bf16 v[36:39], v[172:175], v[196:199], v[36:39]
	v_mfma_f32_16x16x32_bf16 v[32:35], v[180:183], v[196:199], v[32:35]
	v_mfma_f32_16x16x32_bf16 v[20:23], v[172:175], v[204:207], v[20:23]
	v_mfma_f32_16x16x32_bf16 v[16:19], v[180:183], v[204:207], v[16:19]
	v_mfma_f32_16x16x32_bf16 v[4:7], v[172:175], v[212:215], v[4:7]
	v_mfma_f32_16x16x32_bf16 v[0:3], v[180:183], v[212:215], v[0:3]
	s_barrier
	s_add_i32 s37, 0, 0x18000
	s_add_i32 s42, 0, 0x1c000
	v_add_u32_e32 v164, s37, v151
	v_add_u32_e32 v180, s42, v151
	ds_read_b128 v[144:147], v164
	ds_read_b128 v[156:159], v164 offset:1024
	ds_read_b128 v[160:163], v164 offset:2048
	ds_read_b128 v[164:167], v164 offset:3072
	ds_read_b128 v[168:171], v180
	ds_read_b128 v[172:175], v180 offset:1024
	ds_read_b128 v[176:179], v180 offset:2048
	ds_read_b128 v[180:183], v180 offset:3072
	s_add_u32 s40, s48, 0x100000
	s_addc_u32 s41, s49, 0
	s_mov_b32 m0, s53
	ds_read_b128 v[184:187], v155 offset:32768
	ds_read_b128 v[188:191], v155 offset:33792
	ds_read_b128 v[192:195], v155 offset:34816
	ds_read_b128 v[196:199], v155 offset:35840
	ds_read_b128 v[200:203], v155 offset:36864
	ds_read_b128 v[204:207], v155 offset:37888
	ds_read_b128 v[208:211], v155 offset:38912
	ds_read_b128 v[212:215], v155 offset:39936
	global_load_lds_dwordx4 v128, s[40:41]
	s_mov_b32 m0, s54
	s_nop 0
	global_load_lds_dwordx4 v132, s[40:41]
	s_waitcnt vmcnt(8)
	s_waitcnt lgkmcnt(0)
	s_barrier
	s_waitcnt lgkmcnt(0)
	v_mfma_f32_16x16x32_bf16 v[124:127], v[144:147], v[184:187], v[124:127]
	v_mfma_f32_16x16x32_bf16 v[120:123], v[160:163], v[184:187], v[120:123]
	v_mfma_f32_16x16x32_bf16 v[108:111], v[144:147], v[192:195], v[108:111]
	v_mfma_f32_16x16x32_bf16 v[104:107], v[160:163], v[192:195], v[104:107]
	v_mfma_f32_16x16x32_bf16 v[92:95], v[144:147], v[200:203], v[92:95]
	v_mfma_f32_16x16x32_bf16 v[88:91], v[160:163], v[200:203], v[88:91]
	v_mfma_f32_16x16x32_bf16 v[76:79], v[144:147], v[208:211], v[76:79]
	v_mfma_f32_16x16x32_bf16 v[72:75], v[160:163], v[208:211], v[72:75]
	v_mfma_f32_16x16x32_bf16 v[124:127], v[156:159], v[188:191], v[124:127]
	v_mfma_f32_16x16x32_bf16 v[120:123], v[164:167], v[188:191], v[120:123]
	v_mfma_f32_16x16x32_bf16 v[108:111], v[156:159], v[196:199], v[108:111]
	v_mfma_f32_16x16x32_bf16 v[104:107], v[164:167], v[196:199], v[104:107]
	v_mfma_f32_16x16x32_bf16 v[92:95], v[156:159], v[204:207], v[92:95]
	v_mfma_f32_16x16x32_bf16 v[88:91], v[164:167], v[204:207], v[88:91]
	v_mfma_f32_16x16x32_bf16 v[76:79], v[156:159], v[212:215], v[76:79]
	v_mfma_f32_16x16x32_bf16 v[72:75], v[164:167], v[212:215], v[72:75]
	v_mfma_f32_16x16x32_bf16 v[116:119], v[168:171], v[184:187], v[116:119]
	v_mfma_f32_16x16x32_bf16 v[112:115], v[176:179], v[184:187], v[112:115]
	v_mfma_f32_16x16x32_bf16 v[100:103], v[168:171], v[192:195], v[100:103]
	v_mfma_f32_16x16x32_bf16 v[96:99], v[176:179], v[192:195], v[96:99]
	v_mfma_f32_16x16x32_bf16 v[84:87], v[168:171], v[200:203], v[84:87]
	v_mfma_f32_16x16x32_bf16 v[80:83], v[176:179], v[200:203], v[80:83]
	v_mfma_f32_16x16x32_bf16 v[68:71], v[168:171], v[208:211], v[68:71]
	v_mfma_f32_16x16x32_bf16 v[64:67], v[176:179], v[208:211], v[64:67]
	v_mfma_f32_16x16x32_bf16 v[116:119], v[172:175], v[188:191], v[116:119]
	v_mfma_f32_16x16x32_bf16 v[112:115], v[180:183], v[188:191], v[112:115]
	v_mfma_f32_16x16x32_bf16 v[100:103], v[172:175], v[196:199], v[100:103]
	v_mfma_f32_16x16x32_bf16 v[96:99], v[180:183], v[196:199], v[96:99]
	v_mfma_f32_16x16x32_bf16 v[84:87], v[172:175], v[204:207], v[84:87]
	v_mfma_f32_16x16x32_bf16 v[80:83], v[180:183], v[204:207], v[80:83]
	v_mfma_f32_16x16x32_bf16 v[68:71], v[172:175], v[212:215], v[68:71]
	v_mfma_f32_16x16x32_bf16 v[64:67], v[180:183], v[212:215], v[64:67]
	s_barrier
	s_add_i32 s37, s37, s67
	s_mov_b32 m0, s37
	ds_read_b128 v[184:187], v155 offset:49152
	ds_read_b128 v[188:191], v155 offset:50176
	ds_read_b128 v[192:195], v155 offset:51200
	ds_read_b128 v[196:199], v155 offset:52224
	ds_read_b128 v[200:203], v155 offset:53248
	ds_read_b128 v[204:207], v155 offset:54272
	ds_read_b128 v[208:211], v155 offset:55296
	ds_read_b128 v[212:215], v155 offset:56320
	s_add_u32 s100, s46, 0x80
	s_addc_u32 s101, s47, 0
	global_load_lds_dwordx4 v130, s[100:101]
	s_add_i32 m0, s37, 0x2000
	s_add_u32 s40, s46, 0x100080
	s_addc_u32 s41, s47, 0
	s_add_i32 s37, s42, s67
	s_add_u32 s100, s46, 0x80
	s_addc_u32 s101, s47, 0
	global_load_lds_dwordx4 v134, s[100:101]
	s_mov_b32 m0, s37
	s_nop 0
	global_load_lds_dwordx4 v130, s[40:41]
	s_add_i32 m0, s37, 0x2000
	s_nop 0
	global_load_lds_dwordx4 v134, s[40:41]
	s_mov_b32 m0, s56
	s_nop 0
	s_add_u32 s100, s48, 0x80
	s_addc_u32 s101, s49, 0
	global_load_lds_dwordx4 v128, s[100:101]
	s_mov_b32 m0, s57
	s_nop 0
	s_add_u32 s100, s48, 0x80
	s_addc_u32 s101, s49, 0
	global_load_lds_dwordx4 v132, s[100:101]
	s_add_i32 s36, s36, 2
	s_add_u32 s38, s38, 0x100
	s_addc_u32 s39, s39, 0
	s_add_u32 s34, s34, 0x100
	s_addc_u32 s35, s35, 0
	s_cmp_gt_u32 s36, 61
	s_waitcnt vmcnt(8)
	s_waitcnt lgkmcnt(0)
	s_barrier
	s_waitcnt lgkmcnt(0)
	v_mfma_f32_16x16x32_bf16 v[60:63], v[144:147], v[184:187], v[60:63]
	v_mfma_f32_16x16x32_bf16 v[56:59], v[160:163], v[184:187], v[56:59]
	v_mfma_f32_16x16x32_bf16 v[44:47], v[144:147], v[192:195], v[44:47]
	v_mfma_f32_16x16x32_bf16 v[40:43], v[160:163], v[192:195], v[40:43]
	v_mfma_f32_16x16x32_bf16 v[28:31], v[144:147], v[200:203], v[28:31]
	v_mfma_f32_16x16x32_bf16 v[24:27], v[160:163], v[200:203], v[24:27]
	v_mfma_f32_16x16x32_bf16 v[12:15], v[144:147], v[208:211], v[12:15]
	v_mfma_f32_16x16x32_bf16 v[8:11], v[160:163], v[208:211], v[8:11]
	v_mfma_f32_16x16x32_bf16 v[60:63], v[156:159], v[188:191], v[60:63]
	v_mfma_f32_16x16x32_bf16 v[56:59], v[164:167], v[188:191], v[56:59]
	v_mfma_f32_16x16x32_bf16 v[44:47], v[156:159], v[196:199], v[44:47]
	v_mfma_f32_16x16x32_bf16 v[40:43], v[164:167], v[196:199], v[40:43]
	v_mfma_f32_16x16x32_bf16 v[28:31], v[156:159], v[204:207], v[28:31]
	v_mfma_f32_16x16x32_bf16 v[24:27], v[164:167], v[204:207], v[24:27]
	v_mfma_f32_16x16x32_bf16 v[12:15], v[156:159], v[212:215], v[12:15]
	v_mfma_f32_16x16x32_bf16 v[8:11], v[164:167], v[212:215], v[8:11]
	v_mfma_f32_16x16x32_bf16 v[52:55], v[168:171], v[184:187], v[52:55]
	v_mfma_f32_16x16x32_bf16 v[48:51], v[176:179], v[184:187], v[48:51]
	v_mfma_f32_16x16x32_bf16 v[36:39], v[168:171], v[192:195], v[36:39]
	v_mfma_f32_16x16x32_bf16 v[32:35], v[176:179], v[192:195], v[32:35]
	v_mfma_f32_16x16x32_bf16 v[20:23], v[168:171], v[200:203], v[20:23]
	v_mfma_f32_16x16x32_bf16 v[16:19], v[176:179], v[200:203], v[16:19]
	v_mfma_f32_16x16x32_bf16 v[4:7], v[168:171], v[208:211], v[4:7]
	v_mfma_f32_16x16x32_bf16 v[0:3], v[176:179], v[208:211], v[0:3]
	v_mfma_f32_16x16x32_bf16 v[52:55], v[172:175], v[188:191], v[52:55]
	v_mfma_f32_16x16x32_bf16 v[48:51], v[180:183], v[188:191], v[48:51]
	v_mfma_f32_16x16x32_bf16 v[36:39], v[172:175], v[196:199], v[36:39]
	v_mfma_f32_16x16x32_bf16 v[32:35], v[180:183], v[196:199], v[32:35]
	v_mfma_f32_16x16x32_bf16 v[20:23], v[172:175], v[204:207], v[20:23]
	v_mfma_f32_16x16x32_bf16 v[16:19], v[180:183], v[204:207], v[16:19]
	v_mfma_f32_16x16x32_bf16 v[4:7], v[172:175], v[212:215], v[4:7]
	v_mfma_f32_16x16x32_bf16 v[0:3], v[180:183], v[212:215], v[0:3]
	s_barrier
	s_cbranch_scc0 .LBB0_758
	s_setprio 0
	s_and_b64 vcc, exec, s[8:9]
	s_cbranch_vccz .LBB0_761
	s_barrier

.Lmy_prio_skip5:
.LBB0_914:
	ds_read_b128 v[128:131], v187
	ds_read_b128 v[132:135], v187 offset:1024
	ds_read_b128 v[136:139], v187 offset:2048
	ds_read_b128 v[140:143], v187 offset:3072
	ds_read_b128 v[144:147], v188
	ds_read_b128 v[148:151], v188 offset:1024
	ds_read_b128 v[152:155], v188 offset:2048
	ds_read_b128 v[156:159], v188 offset:3072
	s_add_u32 s52, s50, 0x100
	s_addc_u32 s53, s51, 0
	s_cmp_eq_u32 s96, 60
	s_cselect_b32 s57, s41, s53
	s_cselect_b32 s56, s47, s52
	s_cselect_b32 s55, s39, s49
	s_cselect_b32 s54, s34, s35
	s_add_i32 m0, s67, 0xc000
	ds_read_b128 v[178:181], v189
	ds_read_b128 v[192:195], v189 offset:1024
	ds_read_b128 v[196:199], v189 offset:2048
	ds_read_b128 v[200:203], v189 offset:3072
	ds_read_b128 v[204:207], v189 offset:4096
	ds_read_b128 v[208:211], v189 offset:5120
	ds_read_b128 v[212:215], v189 offset:6144
	ds_read_b128 v[216:219], v189 offset:7168
	global_load_lds_dwordx4 v170, s[50:51]
	s_add_i32 m0, s67, 0xe000
	s_nop 0
	global_load_lds_dwordx4 v172, s[50:51]
	s_waitcnt vmcnt(8)
	s_waitcnt lgkmcnt(0)
	s_barrier
	s_waitcnt lgkmcnt(0)
	v_mfma_f32_16x16x32_bf16 v[124:127], v[128:131], v[178:181], v[124:127]
	v_mfma_f32_16x16x32_bf16 v[60:63], v[136:139], v[178:181], v[60:63]
	v_mfma_f32_16x16x32_bf16 v[116:119], v[128:131], v[196:199], v[116:119]
	v_mfma_f32_16x16x32_bf16 v[56:59], v[136:139], v[196:199], v[56:59]
	v_mfma_f32_16x16x32_bf16 v[108:111], v[128:131], v[204:207], v[108:111]
	v_mfma_f32_16x16x32_bf16 v[44:47], v[136:139], v[204:207], v[44:47]
	v_mfma_f32_16x16x32_bf16 v[104:107], v[128:131], v[212:215], v[104:107]
	v_mfma_f32_16x16x32_bf16 v[40:43], v[136:139], v[212:215], v[40:43]
	v_mfma_f32_16x16x32_bf16 v[124:127], v[132:135], v[192:195], v[124:127]
	v_mfma_f32_16x16x32_bf16 v[60:63], v[140:143], v[192:195], v[60:63]
	v_mfma_f32_16x16x32_bf16 v[116:119], v[132:135], v[200:203], v[116:119]
	v_mfma_f32_16x16x32_bf16 v[56:59], v[140:143], v[200:203], v[56:59]
	v_mfma_f32_16x16x32_bf16 v[108:111], v[132:135], v[208:211], v[108:111]
	v_mfma_f32_16x16x32_bf16 v[44:47], v[140:143], v[208:211], v[44:47]
	v_mfma_f32_16x16x32_bf16 v[104:107], v[132:135], v[216:219], v[104:107]
	v_mfma_f32_16x16x32_bf16 v[40:43], v[140:143], v[216:219], v[40:43]
	v_mfma_f32_16x16x32_bf16 v[120:123], v[144:147], v[178:181], v[120:123]
	v_mfma_f32_16x16x32_bf16 v[52:55], v[152:155], v[178:181], v[52:55]
	v_mfma_f32_16x16x32_bf16 v[112:115], v[144:147], v[196:199], v[112:115]
	v_mfma_f32_16x16x32_bf16 v[48:51], v[152:155], v[196:199], v[48:51]
	v_mfma_f32_16x16x32_bf16 v[100:103], v[144:147], v[204:207], v[100:103]
	v_mfma_f32_16x16x32_bf16 v[36:39], v[152:155], v[204:207], v[36:39]
	v_mfma_f32_16x16x32_bf16 v[96:99], v[144:147], v[212:215], v[96:99]
	v_mfma_f32_16x16x32_bf16 v[32:35], v[152:155], v[212:215], v[32:35]
	v_mfma_f32_16x16x32_bf16 v[120:123], v[148:151], v[192:195], v[120:123]
	v_mfma_f32_16x16x32_bf16 v[52:55], v[156:159], v[192:195], v[52:55]
	v_mfma_f32_16x16x32_bf16 v[112:115], v[148:151], v[200:203], v[112:115]
	v_mfma_f32_16x16x32_bf16 v[48:51], v[156:159], v[200:203], v[48:51]
	v_mfma_f32_16x16x32_bf16 v[100:103], v[148:151], v[208:211], v[100:103]
	v_mfma_f32_16x16x32_bf16 v[36:39], v[156:159], v[208:211], v[36:39]
	v_mfma_f32_16x16x32_bf16 v[96:99], v[148:151], v[216:219], v[96:99]
	v_mfma_f32_16x16x32_bf16 v[32:35], v[156:159], v[216:219], v[32:35]
	s_barrier
	s_add_i32 s50, s92, s66
	s_mov_b32 m0, s50
	ds_read_b128 v[178:181], v189 offset:16384
	ds_read_b128 v[192:195], v189 offset:17408
	ds_read_b128 v[196:199], v189 offset:18432
	ds_read_b128 v[200:203], v189 offset:19456
	ds_read_b128 v[204:207], v189 offset:20480
	ds_read_b128 v[208:211], v189 offset:21504
	ds_read_b128 v[212:215], v189 offset:22528
	ds_read_b128 v[216:219], v189 offset:23552
	global_load_lds_dwordx4 v164, s[54:55]
	s_add_i32 m0, s50, 0x2000
	s_add_u32 s50, s54, 0x100000
	v_lshl_add_u64 v[182:183], s[54:55], 0, v[168:169]
	s_addc_u32 s51, s55, 0
	s_add_i32 s97, s93, s66
	global_load_lds_dwordx4 v168, s[54:55]
	s_mov_b32 m0, s97
	global_load_lds_dwordx4 v164, s[50:51]
	s_add_i32 m0, s97, 0x2000
	s_nop 0
	global_load_lds_dwordx4 v168, s[50:51]
	s_mov_b32 m0, s67
	s_nop 0
	global_load_lds_dwordx4 v162, s[56:57]
	s_mov_b32 m0, s68
	s_nop 0
	global_load_lds_dwordx4 v166, s[56:57]
	s_waitcnt vmcnt(8)
	s_waitcnt lgkmcnt(0)
	s_barrier
	s_waitcnt lgkmcnt(0)
	v_mfma_f32_16x16x32_bf16 v[92:95], v[128:131], v[178:181], v[92:95]
	v_mfma_f32_16x16x32_bf16 v[28:31], v[136:139], v[178:181], v[28:31]
	v_mfma_f32_16x16x32_bf16 v[84:87], v[128:131], v[196:199], v[84:87]
	v_mfma_f32_16x16x32_bf16 v[24:27], v[136:139], v[196:199], v[24:27]
	v_mfma_f32_16x16x32_bf16 v[76:79], v[128:131], v[204:207], v[76:79]
	v_mfma_f32_16x16x32_bf16 v[12:15], v[136:139], v[204:207], v[12:15]
	v_mfma_f32_16x16x32_bf16 v[72:75], v[128:131], v[212:215], v[72:75]
	v_mfma_f32_16x16x32_bf16 v[8:11], v[136:139], v[212:215], v[8:11]
	v_mfma_f32_16x16x32_bf16 v[92:95], v[132:135], v[192:195], v[92:95]
	v_mfma_f32_16x16x32_bf16 v[28:31], v[140:143], v[192:195], v[28:31]
	v_mfma_f32_16x16x32_bf16 v[84:87], v[132:135], v[200:203], v[84:87]
	v_mfma_f32_16x16x32_bf16 v[24:27], v[140:143], v[200:203], v[24:27]
	v_mfma_f32_16x16x32_bf16 v[76:79], v[132:135], v[208:211], v[76:79]
	v_mfma_f32_16x16x32_bf16 v[12:15], v[140:143], v[208:211], v[12:15]
	v_mfma_f32_16x16x32_bf16 v[72:75], v[132:135], v[216:219], v[72:75]
	v_mfma_f32_16x16x32_bf16 v[8:11], v[140:143], v[216:219], v[8:11]
	v_mfma_f32_16x16x32_bf16 v[88:91], v[144:147], v[178:181], v[88:91]
	v_mfma_f32_16x16x32_bf16 v[20:23], v[152:155], v[178:181], v[20:23]
	v_mfma_f32_16x16x32_bf16 v[80:83], v[144:147], v[196:199], v[80:83]
	v_mfma_f32_16x16x32_bf16 v[16:19], v[152:155], v[196:199], v[16:19]
	v_mfma_f32_16x16x32_bf16 v[68:71], v[144:147], v[204:207], v[68:71]
	v_mfma_f32_16x16x32_bf16 v[4:7], v[152:155], v[204:207], v[4:7]
	v_mfma_f32_16x16x32_bf16 v[64:67], v[144:147], v[212:215], v[64:67]
	v_mfma_f32_16x16x32_bf16 v[0:3], v[152:155], v[212:215], v[0:3]
	v_mfma_f32_16x16x32_bf16 v[88:91], v[148:151], v[192:195], v[88:91]
	v_mfma_f32_16x16x32_bf16 v[20:23], v[156:159], v[192:195], v[20:23]
	v_mfma_f32_16x16x32_bf16 v[80:83], v[148:151], v[200:203], v[80:83]
	v_mfma_f32_16x16x32_bf16 v[16:19], v[156:159], v[200:203], v[16:19]
	v_mfma_f32_16x16x32_bf16 v[68:71], v[148:151], v[208:211], v[68:71]
	v_mfma_f32_16x16x32_bf16 v[4:7], v[156:159], v[208:211], v[4:7]
	v_mfma_f32_16x16x32_bf16 v[64:67], v[148:151], v[216:219], v[64:67]
	v_mfma_f32_16x16x32_bf16 v[0:3], v[156:159], v[216:219], v[0:3]
	s_barrier
	s_add_i32 s97, 0, 0x18000
	s_add_i32 vcc_lo, 0, 0x1c000
	v_add_u32_e32 v140, s97, v184
	v_add_u32_e32 v156, vcc_lo, v184
	ds_read_b128 v[128:131], v140
	ds_read_b128 v[132:135], v140 offset:1024
	ds_read_b128 v[136:139], v140 offset:2048
	ds_read_b128 v[140:143], v140 offset:3072
	ds_read_b128 v[144:147], v156
	ds_read_b128 v[148:151], v156 offset:1024
	ds_read_b128 v[152:155], v156 offset:2048
	ds_read_b128 v[156:159], v156 offset:3072
	s_add_u32 s50, s56, 0x100000
	s_addc_u32 s51, s57, 0
	s_mov_b32 m0, s69
	ds_read_b128 v[178:181], v189 offset:32768
	ds_read_b128 v[192:195], v189 offset:33792
	ds_read_b128 v[196:199], v189 offset:34816
	ds_read_b128 v[200:203], v189 offset:35840
	ds_read_b128 v[204:207], v189 offset:36864
	ds_read_b128 v[208:211], v189 offset:37888
	ds_read_b128 v[212:215], v189 offset:38912
	ds_read_b128 v[216:219], v189 offset:39936
	global_load_lds_dwordx4 v162, s[50:51]
	s_mov_b32 m0, s76
	s_nop 0
	global_load_lds_dwordx4 v166, s[50:51]
	s_waitcnt vmcnt(8)
	s_waitcnt lgkmcnt(0)
	s_barrier
	s_waitcnt lgkmcnt(0)
	v_mfma_f32_16x16x32_bf16 v[124:127], v[128:131], v[178:181], v[124:127]
	v_mfma_f32_16x16x32_bf16 v[60:63], v[136:139], v[178:181], v[60:63]
	v_mfma_f32_16x16x32_bf16 v[116:119], v[128:131], v[196:199], v[116:119]
	v_mfma_f32_16x16x32_bf16 v[56:59], v[136:139], v[196:199], v[56:59]
	v_mfma_f32_16x16x32_bf16 v[108:111], v[128:131], v[204:207], v[108:111]
	v_mfma_f32_16x16x32_bf16 v[44:47], v[136:139], v[204:207], v[44:47]
	v_mfma_f32_16x16x32_bf16 v[104:107], v[128:131], v[212:215], v[104:107]
	v_mfma_f32_16x16x32_bf16 v[40:43], v[136:139], v[212:215], v[40:43]
	v_mfma_f32_16x16x32_bf16 v[124:127], v[132:135], v[192:195], v[124:127]
	v_mfma_f32_16x16x32_bf16 v[60:63], v[140:143], v[192:195], v[60:63]
	v_mfma_f32_16x16x32_bf16 v[116:119], v[132:135], v[200:203], v[116:119]
	v_mfma_f32_16x16x32_bf16 v[56:59], v[140:143], v[200:203], v[56:59]
	v_mfma_f32_16x16x32_bf16 v[108:111], v[132:135], v[208:211], v[108:111]
	v_mfma_f32_16x16x32_bf16 v[44:47], v[140:143], v[208:211], v[44:47]
	v_mfma_f32_16x16x32_bf16 v[104:107], v[132:135], v[216:219], v[104:107]
	v_mfma_f32_16x16x32_bf16 v[40:43], v[140:143], v[216:219], v[40:43]
	v_mfma_f32_16x16x32_bf16 v[120:123], v[144:147], v[178:181], v[120:123]
	v_mfma_f32_16x16x32_bf16 v[52:55], v[152:155], v[178:181], v[52:55]
	v_mfma_f32_16x16x32_bf16 v[112:115], v[144:147], v[196:199], v[112:115]
	v_mfma_f32_16x16x32_bf16 v[48:51], v[152:155], v[196:199], v[48:51]
	v_mfma_f32_16x16x32_bf16 v[100:103], v[144:147], v[204:207], v[100:103]
	v_mfma_f32_16x16x32_bf16 v[36:39], v[152:155], v[204:207], v[36:39]
	v_mfma_f32_16x16x32_bf16 v[96:99], v[144:147], v[212:215], v[96:99]
	v_mfma_f32_16x16x32_bf16 v[32:35], v[152:155], v[212:215], v[32:35]
	v_mfma_f32_16x16x32_bf16 v[120:123], v[148:151], v[192:195], v[120:123]
	v_mfma_f32_16x16x32_bf16 v[52:55], v[156:159], v[192:195], v[52:55]
	v_mfma_f32_16x16x32_bf16 v[112:115], v[148:151], v[200:203], v[112:115]
	v_mfma_f32_16x16x32_bf16 v[48:51], v[156:159], v[200:203], v[48:51]
	v_mfma_f32_16x16x32_bf16 v[100:103], v[148:151], v[208:211], v[100:103]
	v_mfma_f32_16x16x32_bf16 v[36:39], v[156:159], v[208:211], v[36:39]
	v_mfma_f32_16x16x32_bf16 v[96:99], v[148:151], v[216:219], v[96:99]
	v_mfma_f32_16x16x32_bf16 v[32:35], v[156:159], v[216:219], v[32:35]
	s_barrier
	s_add_i32 s50, s97, s66
	s_mov_b32 m0, s50
	ds_read_b128 v[178:181], v189 offset:49152
	ds_read_b128 v[192:195], v189 offset:50176
	ds_read_b128 v[196:199], v189 offset:51200
	ds_read_b128 v[200:203], v189 offset:52224
	ds_read_b128 v[204:207], v189 offset:53248
	ds_read_b128 v[208:211], v189 offset:54272
	ds_read_b128 v[212:215], v189 offset:55296
	ds_read_b128 v[216:219], v189 offset:56320
	s_add_u32 s100, s54, 0x80
	s_addc_u32 s101, s55, 0
	global_load_lds_dwordx4 v164, s[100:101]
	s_add_i32 m0, s50, 0x2000
	s_add_u32 s50, s54, 0x100080
	v_lshl_add_u64 v[160:161], v[182:183], 0, s[10:11]
	s_addc_u32 s51, s55, 0
	s_add_i32 s54, vcc_lo, s66
	global_load_lds_dwordx4 v[160:161], off
	s_mov_b32 m0, s54
	s_nop 0
	global_load_lds_dwordx4 v164, s[50:51]
	s_add_i32 m0, s54, 0x2000
	s_nop 0
	global_load_lds_dwordx4 v168, s[50:51]
	s_mov_b32 m0, s84
	s_nop 0
	s_add_u32 s100, s56, 0x80
	s_addc_u32 s101, s57, 0
	global_load_lds_dwordx4 v162, s[100:101]
	s_mov_b32 m0, s85
	s_nop 0
	s_add_u32 s100, s56, 0x80
	s_addc_u32 s101, s57, 0
	global_load_lds_dwordx4 v166, s[100:101]
	s_add_i32 s96, s96, 2
	s_add_u32 s35, s35, 0x100
	s_addc_u32 s49, s49, 0
	s_cmp_gt_u32 s96, 61
	s_waitcnt vmcnt(8)
	s_waitcnt lgkmcnt(0)
	s_barrier
	s_waitcnt lgkmcnt(0)
	v_mfma_f32_16x16x32_bf16 v[92:95], v[128:131], v[178:181], v[92:95]
	v_mfma_f32_16x16x32_bf16 v[28:31], v[136:139], v[178:181], v[28:31]
	v_mfma_f32_16x16x32_bf16 v[84:87], v[128:131], v[196:199], v[84:87]
	v_mfma_f32_16x16x32_bf16 v[24:27], v[136:139], v[196:199], v[24:27]
	v_mfma_f32_16x16x32_bf16 v[76:79], v[128:131], v[204:207], v[76:79]
	v_mfma_f32_16x16x32_bf16 v[12:15], v[136:139], v[204:207], v[12:15]
	v_mfma_f32_16x16x32_bf16 v[72:75], v[128:131], v[212:215], v[72:75]
	v_mfma_f32_16x16x32_bf16 v[8:11], v[136:139], v[212:215], v[8:11]
	v_mfma_f32_16x16x32_bf16 v[92:95], v[132:135], v[192:195], v[92:95]
	v_mfma_f32_16x16x32_bf16 v[28:31], v[140:143], v[192:195], v[28:31]
	v_mfma_f32_16x16x32_bf16 v[84:87], v[132:135], v[200:203], v[84:87]
	v_mfma_f32_16x16x32_bf16 v[24:27], v[140:143], v[200:203], v[24:27]
	v_mfma_f32_16x16x32_bf16 v[76:79], v[132:135], v[208:211], v[76:79]
	v_mfma_f32_16x16x32_bf16 v[12:15], v[140:143], v[208:211], v[12:15]
	v_mfma_f32_16x16x32_bf16 v[72:75], v[132:135], v[216:219], v[72:75]
	v_mfma_f32_16x16x32_bf16 v[8:11], v[140:143], v[216:219], v[8:11]
	v_mfma_f32_16x16x32_bf16 v[88:91], v[144:147], v[178:181], v[88:91]
	v_mfma_f32_16x16x32_bf16 v[20:23], v[152:155], v[178:181], v[20:23]
	v_mfma_f32_16x16x32_bf16 v[80:83], v[144:147], v[196:199], v[80:83]
	v_mfma_f32_16x16x32_bf16 v[16:19], v[152:155], v[196:199], v[16:19]
	v_mfma_f32_16x16x32_bf16 v[68:71], v[144:147], v[204:207], v[68:71]
	v_mfma_f32_16x16x32_bf16 v[4:7], v[152:155], v[204:207], v[4:7]
	v_mfma_f32_16x16x32_bf16 v[64:67], v[144:147], v[212:215], v[64:67]
	v_mfma_f32_16x16x32_bf16 v[0:3], v[152:155], v[212:215], v[0:3]
	v_mfma_f32_16x16x32_bf16 v[88:91], v[148:151], v[192:195], v[88:91]
	v_mfma_f32_16x16x32_bf16 v[20:23], v[156:159], v[192:195], v[20:23]
	v_mfma_f32_16x16x32_bf16 v[80:83], v[148:151], v[200:203], v[80:83]
	v_mfma_f32_16x16x32_bf16 v[16:19], v[156:159], v[200:203], v[16:19]
	v_mfma_f32_16x16x32_bf16 v[68:71], v[148:151], v[208:211], v[68:71]
	v_mfma_f32_16x16x32_bf16 v[4:7], v[156:159], v[208:211], v[4:7]
	v_mfma_f32_16x16x32_bf16 v[64:67], v[148:151], v[216:219], v[64:67]
	v_mfma_f32_16x16x32_bf16 v[0:3], v[156:159], v[216:219], v[0:3]
	s_barrier
	s_mov_b64 s[50:51], s[52:53]
	s_cbranch_scc0 .LBB0_914
	s_setprio 0
	s_lshl_b32 s34, s46, 2
	v_lshl_or_b32 v178, s48, 7, v186
	s_add_i32 s34, s34, s65
	v_ashrrev_i32_e32 v179, 31, v178
	s_mul_hi_i32 s35, s34, 0x30000
	s_mul_i32 s39, s34, 0x30000
	s_and_saveexec_b64 s[48:49], s[0:1]
	s_cbranch_execz .LBB0_917
	s_add_u32 s50, s79, s39
	s_addc_u32 s51, s81, s35
	v_lshl_add_u64 v[132:133], v[178:179], 1, s[50:51]
	v_add_co_u32_e32 v134, vcc, s78, v132
	s_nop 2
	v_cvt_pk_bf16_f32 v128, v124, v125
	s_nop 2
	v_cvt_pk_bf16_f32 v129, v126, v127
	s_nop 2
	v_cvt_pk_bf16_f32 v130, v60, v61
	s_nop 2
	v_cvt_pk_bf16_f32 v131, v62, v63
	s_nop 1
	v_addc_co_u32_e32 v135, vcc, 0, v133, vcc
	s_mov_b32 s17, 0xc000
	global_store_dwordx4 v[132:133], v[128:131], off
	s_nop 1
	s_nop 2
	v_cvt_pk_bf16_f32 v128, v120, v121
	s_nop 2
	v_cvt_pk_bf16_f32 v129, v122, v123
	s_nop 2
	v_cvt_pk_bf16_f32 v130, v52, v53
	s_nop 2
	v_cvt_pk_bf16_f32 v131, v54, v55
	global_store_dwordx4 v[134:135], v[128:131], off
	v_add_co_u32_e32 v134, vcc, s17, v132
	s_nop 0
	s_nop 2
	v_cvt_pk_bf16_f32 v128, v116, v117
	s_nop 2
	v_cvt_pk_bf16_f32 v129, v118, v119
	s_nop 2
	v_cvt_pk_bf16_f32 v130, v56, v57
	s_nop 2
	v_cvt_pk_bf16_f32 v131, v58, v59
	s_nop 0
	v_addc_co_u32_e32 v135, vcc, 0, v133, vcc
	v_add_co_u32_e32 v132, vcc, 0x12000, v132
	global_store_dwordx4 v[134:135], v[128:131], off
	s_nop 0
	v_addc_co_u32_e32 v133, vcc, 0, v133, vcc
	s_nop 2
	v_cvt_pk_bf16_f32 v128, v112, v113
	s_nop 2
	v_cvt_pk_bf16_f32 v129, v114, v115
	s_nop 2
	v_cvt_pk_bf16_f32 v130, v48, v49
	s_nop 2
	v_cvt_pk_bf16_f32 v131, v50, v51
	global_store_dwordx4 v[132:133], v[128:131], off

.Lmy_prio_skip6:
.LBB0_1077:
	ds_read_b128 v[144:147], v153
	ds_read_b128 v[156:159], v153 offset:1024
	ds_read_b128 v[160:163], v153 offset:2048
	ds_read_b128 v[164:167], v153 offset:3072
	ds_read_b128 v[168:171], v154
	ds_read_b128 v[172:175], v154 offset:1024
	ds_read_b128 v[176:179], v154 offset:2048
	ds_read_b128 v[180:183], v154 offset:3072
	s_add_u32 s28, s26, 0x100
	s_addc_u32 s29, s27, 0
	s_cmpk_eq_i32 s53, 0xbc
	s_cselect_b32 s37, s3, s29
	s_cselect_b32 s36, s2, s28
	s_cselect_b32 s31, s25, s35
	s_cselect_b32 s30, s24, s34
	s_add_i32 m0, s39, 0xc000
	ds_read_b128 v[184:187], v155
	ds_read_b128 v[188:191], v155 offset:1024
	ds_read_b128 v[192:195], v155 offset:2048
	ds_read_b128 v[196:199], v155 offset:3072
	ds_read_b128 v[200:203], v155 offset:4096
	ds_read_b128 v[204:207], v155 offset:5120
	ds_read_b128 v[208:211], v155 offset:6144
	ds_read_b128 v[212:215], v155 offset:7168
	global_load_lds_dwordx4 v136, s[26:27]
	s_add_i32 m0, s39, 0xe000
	s_nop 0
	global_load_lds_dwordx4 v138, s[26:27]
	s_waitcnt vmcnt(8)
	s_waitcnt lgkmcnt(0)
	s_barrier
	s_waitcnt lgkmcnt(0)
	v_mfma_f32_16x16x32_bf16 v[124:127], v[144:147], v[184:187], v[124:127]
	v_mfma_f32_16x16x32_bf16 v[120:123], v[160:163], v[184:187], v[120:123]
	v_mfma_f32_16x16x32_bf16 v[108:111], v[144:147], v[192:195], v[108:111]
	v_mfma_f32_16x16x32_bf16 v[104:107], v[160:163], v[192:195], v[104:107]
	v_mfma_f32_16x16x32_bf16 v[92:95], v[144:147], v[200:203], v[92:95]
	v_mfma_f32_16x16x32_bf16 v[88:91], v[160:163], v[200:203], v[88:91]
	v_mfma_f32_16x16x32_bf16 v[76:79], v[144:147], v[208:211], v[76:79]
	v_mfma_f32_16x16x32_bf16 v[72:75], v[160:163], v[208:211], v[72:75]
	v_mfma_f32_16x16x32_bf16 v[124:127], v[156:159], v[188:191], v[124:127]
	v_mfma_f32_16x16x32_bf16 v[120:123], v[164:167], v[188:191], v[120:123]
	v_mfma_f32_16x16x32_bf16 v[108:111], v[156:159], v[196:199], v[108:111]
	v_mfma_f32_16x16x32_bf16 v[104:107], v[164:167], v[196:199], v[104:107]
	v_mfma_f32_16x16x32_bf16 v[92:95], v[156:159], v[204:207], v[92:95]
	v_mfma_f32_16x16x32_bf16 v[88:91], v[164:167], v[204:207], v[88:91]
	v_mfma_f32_16x16x32_bf16 v[76:79], v[156:159], v[212:215], v[76:79]
	v_mfma_f32_16x16x32_bf16 v[72:75], v[164:167], v[212:215], v[72:75]
	v_mfma_f32_16x16x32_bf16 v[116:119], v[168:171], v[184:187], v[116:119]
	v_mfma_f32_16x16x32_bf16 v[112:115], v[176:179], v[184:187], v[112:115]
	v_mfma_f32_16x16x32_bf16 v[100:103], v[168:171], v[192:195], v[100:103]
	v_mfma_f32_16x16x32_bf16 v[96:99], v[176:179], v[192:195], v[96:99]
	v_mfma_f32_16x16x32_bf16 v[84:87], v[168:171], v[200:203], v[84:87]
	v_mfma_f32_16x16x32_bf16 v[80:83], v[176:179], v[200:203], v[80:83]
	v_mfma_f32_16x16x32_bf16 v[68:71], v[168:171], v[208:211], v[68:71]
	v_mfma_f32_16x16x32_bf16 v[64:67], v[176:179], v[208:211], v[64:67]
	v_mfma_f32_16x16x32_bf16 v[116:119], v[172:175], v[188:191], v[116:119]
	v_mfma_f32_16x16x32_bf16 v[112:115], v[180:183], v[188:191], v[112:115]
	v_mfma_f32_16x16x32_bf16 v[100:103], v[172:175], v[196:199], v[100:103]
	v_mfma_f32_16x16x32_bf16 v[96:99], v[180:183], v[196:199], v[96:99]
	v_mfma_f32_16x16x32_bf16 v[84:87], v[172:175], v[204:207], v[84:87]
	v_mfma_f32_16x16x32_bf16 v[80:83], v[180:183], v[204:207], v[80:83]
	v_mfma_f32_16x16x32_bf16 v[68:71], v[172:175], v[212:215], v[68:71]
	v_mfma_f32_16x16x32_bf16 v[64:67], v[180:183], v[212:215], v[64:67]
	s_barrier
	s_add_i32 s26, s47, s38
	s_mov_b32 m0, s26
	ds_read_b128 v[184:187], v155 offset:16384
	ds_read_b128 v[188:191], v155 offset:17408
	ds_read_b128 v[192:195], v155 offset:18432
	ds_read_b128 v[196:199], v155 offset:19456
	ds_read_b128 v[200:203], v155 offset:20480
	ds_read_b128 v[204:207], v155 offset:21504
	ds_read_b128 v[208:211], v155 offset:22528
	ds_read_b128 v[212:215], v155 offset:23552
	global_load_lds_dwordx4 v130, s[30:31]
	s_add_i32 m0, s26, 0x2000
	s_add_u32 s26, s30, 0x300000
	v_lshl_add_u64 v[216:217], s[30:31], 0, v[134:135]
	s_addc_u32 s27, s31, 0
	s_add_i32 s54, s48, s38
	global_load_lds_dwordx4 v134, s[30:31]
	s_mov_b32 m0, s54
	global_load_lds_dwordx4 v130, s[26:27]
	s_add_i32 m0, s54, 0x2000
	s_nop 0
	global_load_lds_dwordx4 v134, s[26:27]
	s_mov_b32 m0, s39
	s_nop 0
	global_load_lds_dwordx4 v128, s[36:37]
	s_mov_b32 m0, s40
	s_nop 0
	global_load_lds_dwordx4 v132, s[36:37]
	s_waitcnt vmcnt(8)
	s_waitcnt lgkmcnt(0)
	s_barrier
	s_waitcnt lgkmcnt(0)
	v_mfma_f32_16x16x32_bf16 v[60:63], v[144:147], v[184:187], v[60:63]
	v_mfma_f32_16x16x32_bf16 v[56:59], v[160:163], v[184:187], v[56:59]
	v_mfma_f32_16x16x32_bf16 v[44:47], v[144:147], v[192:195], v[44:47]
	v_mfma_f32_16x16x32_bf16 v[40:43], v[160:163], v[192:195], v[40:43]
	v_mfma_f32_16x16x32_bf16 v[28:31], v[144:147], v[200:203], v[28:31]
	v_mfma_f32_16x16x32_bf16 v[24:27], v[160:163], v[200:203], v[24:27]
	v_mfma_f32_16x16x32_bf16 v[12:15], v[144:147], v[208:211], v[12:15]
	v_mfma_f32_16x16x32_bf16 v[8:11], v[160:163], v[208:211], v[8:11]
	v_mfma_f32_16x16x32_bf16 v[60:63], v[156:159], v[188:191], v[60:63]
	v_mfma_f32_16x16x32_bf16 v[56:59], v[164:167], v[188:191], v[56:59]
	v_mfma_f32_16x16x32_bf16 v[44:47], v[156:159], v[196:199], v[44:47]
	v_mfma_f32_16x16x32_bf16 v[40:43], v[164:167], v[196:199], v[40:43]
	v_mfma_f32_16x16x32_bf16 v[28:31], v[156:159], v[204:207], v[28:31]
	v_mfma_f32_16x16x32_bf16 v[24:27], v[164:167], v[204:207], v[24:27]
	v_mfma_f32_16x16x32_bf16 v[12:15], v[156:159], v[212:215], v[12:15]
	v_mfma_f32_16x16x32_bf16 v[8:11], v[164:167], v[212:215], v[8:11]
	v_mfma_f32_16x16x32_bf16 v[52:55], v[168:171], v[184:187], v[52:55]
	v_mfma_f32_16x16x32_bf16 v[48:51], v[176:179], v[184:187], v[48:51]
	v_mfma_f32_16x16x32_bf16 v[36:39], v[168:171], v[192:195], v[36:39]
	v_mfma_f32_16x16x32_bf16 v[32:35], v[176:179], v[192:195], v[32:35]
	v_mfma_f32_16x16x32_bf16 v[20:23], v[168:171], v[200:203], v[20:23]
	v_mfma_f32_16x16x32_bf16 v[16:19], v[176:179], v[200:203], v[16:19]
	v_mfma_f32_16x16x32_bf16 v[4:7], v[168:171], v[208:211], v[4:7]
	v_mfma_f32_16x16x32_bf16 v[0:3], v[176:179], v[208:211], v[0:3]
	v_mfma_f32_16x16x32_bf16 v[52:55], v[172:175], v[188:191], v[52:55]
	v_mfma_f32_16x16x32_bf16 v[48:51], v[180:183], v[188:191], v[48:51]
	v_mfma_f32_16x16x32_bf16 v[36:39], v[172:175], v[196:199], v[36:39]
	v_mfma_f32_16x16x32_bf16 v[32:35], v[180:183], v[196:199], v[32:35]
	v_mfma_f32_16x16x32_bf16 v[20:23], v[172:175], v[204:207], v[20:23]
	v_mfma_f32_16x16x32_bf16 v[16:19], v[180:183], v[204:207], v[16:19]
	v_mfma_f32_16x16x32_bf16 v[4:7], v[172:175], v[212:215], v[4:7]
	v_mfma_f32_16x16x32_bf16 v[0:3], v[180:183], v[212:215], v[0:3]
	s_barrier
	s_add_i32 s54, 0, 0x18000
	s_add_i32 s55, 0, 0x1c000
	v_add_u32_e32 v164, s54, v151
	v_add_u32_e32 v180, s55, v151
	ds_read_b128 v[144:147], v164
	ds_read_b128 v[156:159], v164 offset:1024
	ds_read_b128 v[160:163], v164 offset:2048
	ds_read_b128 v[164:167], v164 offset:3072
	ds_read_b128 v[168:171], v180
	ds_read_b128 v[172:175], v180 offset:1024
	ds_read_b128 v[176:179], v180 offset:2048
	ds_read_b128 v[180:183], v180 offset:3072
	s_add_u32 s26, s36, 0x300000
	s_addc_u32 s27, s37, 0
	s_mov_b32 m0, s41
	ds_read_b128 v[184:187], v155 offset:32768
	ds_read_b128 v[188:191], v155 offset:33792
	ds_read_b128 v[192:195], v155 offset:34816
	ds_read_b128 v[196:199], v155 offset:35840
	ds_read_b128 v[200:203], v155 offset:36864
	ds_read_b128 v[204:207], v155 offset:37888
	ds_read_b128 v[208:211], v155 offset:38912
	ds_read_b128 v[212:215], v155 offset:39936
	global_load_lds_dwordx4 v128, s[26:27]
	s_mov_b32 m0, s42
	s_nop 0
	global_load_lds_dwordx4 v132, s[26:27]
	s_waitcnt vmcnt(8)
	s_waitcnt lgkmcnt(0)
	s_barrier
	s_waitcnt lgkmcnt(0)
	v_mfma_f32_16x16x32_bf16 v[124:127], v[144:147], v[184:187], v[124:127]
	v_mfma_f32_16x16x32_bf16 v[120:123], v[160:163], v[184:187], v[120:123]
	v_mfma_f32_16x16x32_bf16 v[108:111], v[144:147], v[192:195], v[108:111]
	v_mfma_f32_16x16x32_bf16 v[104:107], v[160:163], v[192:195], v[104:107]
	v_mfma_f32_16x16x32_bf16 v[92:95], v[144:147], v[200:203], v[92:95]
	v_mfma_f32_16x16x32_bf16 v[88:91], v[160:163], v[200:203], v[88:91]
	v_mfma_f32_16x16x32_bf16 v[76:79], v[144:147], v[208:211], v[76:79]
	v_mfma_f32_16x16x32_bf16 v[72:75], v[160:163], v[208:211], v[72:75]
	v_mfma_f32_16x16x32_bf16 v[124:127], v[156:159], v[188:191], v[124:127]
	v_mfma_f32_16x16x32_bf16 v[120:123], v[164:167], v[188:191], v[120:123]
	v_mfma_f32_16x16x32_bf16 v[108:111], v[156:159], v[196:199], v[108:111]
	v_mfma_f32_16x16x32_bf16 v[104:107], v[164:167], v[196:199], v[104:107]
	v_mfma_f32_16x16x32_bf16 v[92:95], v[156:159], v[204:207], v[92:95]
	v_mfma_f32_16x16x32_bf16 v[88:91], v[164:167], v[204:207], v[88:91]
	v_mfma_f32_16x16x32_bf16 v[76:79], v[156:159], v[212:215], v[76:79]
	v_mfma_f32_16x16x32_bf16 v[72:75], v[164:167], v[212:215], v[72:75]
	v_mfma_f32_16x16x32_bf16 v[116:119], v[168:171], v[184:187], v[116:119]
	v_mfma_f32_16x16x32_bf16 v[112:115], v[176:179], v[184:187], v[112:115]
	v_mfma_f32_16x16x32_bf16 v[100:103], v[168:171], v[192:195], v[100:103]
	v_mfma_f32_16x16x32_bf16 v[96:99], v[176:179], v[192:195], v[96:99]
	v_mfma_f32_16x16x32_bf16 v[84:87], v[168:171], v[200:203], v[84:87]
	v_mfma_f32_16x16x32_bf16 v[80:83], v[176:179], v[200:203], v[80:83]
	v_mfma_f32_16x16x32_bf16 v[68:71], v[168:171], v[208:211], v[68:71]
	v_mfma_f32_16x16x32_bf16 v[64:67], v[176:179], v[208:211], v[64:67]
	v_mfma_f32_16x16x32_bf16 v[116:119], v[172:175], v[188:191], v[116:119]
	v_mfma_f32_16x16x32_bf16 v[112:115], v[180:183], v[188:191], v[112:115]
	v_mfma_f32_16x16x32_bf16 v[100:103], v[172:175], v[196:199], v[100:103]
	v_mfma_f32_16x16x32_bf16 v[96:99], v[180:183], v[196:199], v[96:99]
	v_mfma_f32_16x16x32_bf16 v[84:87], v[172:175], v[204:207], v[84:87]
	v_mfma_f32_16x16x32_bf16 v[80:83], v[180:183], v[204:207], v[80:83]
	v_mfma_f32_16x16x32_bf16 v[68:71], v[172:175], v[212:215], v[68:71]
	v_mfma_f32_16x16x32_bf16 v[64:67], v[180:183], v[212:215], v[64:67]
	s_barrier
	s_add_i32 s26, s54, s38
	s_mov_b32 m0, s26
	ds_read_b128 v[184:187], v155 offset:49152
	ds_read_b128 v[188:191], v155 offset:50176
	ds_read_b128 v[192:195], v155 offset:51200
	ds_read_b128 v[196:199], v155 offset:52224
	ds_read_b128 v[200:203], v155 offset:53248
	ds_read_b128 v[204:207], v155 offset:54272
	ds_read_b128 v[208:211], v155 offset:55296
	ds_read_b128 v[212:215], v155 offset:56320
	s_add_u32 s100, s30, 0x80
	s_addc_u32 s101, s31, 0
	global_load_lds_dwordx4 v130, s[100:101]
	s_add_i32 m0, s26, 0x2000
	s_add_u32 s26, s30, 0x300080
	v_lshl_add_u64 v[148:149], v[216:217], 0, s[10:11]
	s_addc_u32 s27, s31, 0
	s_add_i32 s30, s55, s38
	global_load_lds_dwordx4 v[148:149], off
	s_mov_b32 m0, s30
	s_nop 0
	global_load_lds_dwordx4 v130, s[26:27]
	s_add_i32 m0, s30, 0x2000
	s_nop 0
	global_load_lds_dwordx4 v134, s[26:27]
	s_mov_b32 m0, s44
	s_nop 0
	s_add_u32 s100, s36, 0x80
	s_addc_u32 s101, s37, 0
	global_load_lds_dwordx4 v128, s[100:101]
	s_mov_b32 m0, s45
	s_nop 0
	s_add_u32 s100, s36, 0x80
	s_addc_u32 s101, s37, 0
	global_load_lds_dwordx4 v132, s[100:101]
	s_add_i32 s53, s53, 2
	s_add_u32 s34, s34, 0x100
	s_addc_u32 s35, s35, 0
	s_cmpk_gt_u32 s53, 0xbd
	s_waitcnt vmcnt(8)
	s_waitcnt lgkmcnt(0)
	s_barrier
	s_waitcnt lgkmcnt(0)
	v_mfma_f32_16x16x32_bf16 v[60:63], v[144:147], v[184:187], v[60:63]
	v_mfma_f32_16x16x32_bf16 v[56:59], v[160:163], v[184:187], v[56:59]
	v_mfma_f32_16x16x32_bf16 v[44:47], v[144:147], v[192:195], v[44:47]
	v_mfma_f32_16x16x32_bf16 v[40:43], v[160:163], v[192:195], v[40:43]
	v_mfma_f32_16x16x32_bf16 v[28:31], v[144:147], v[200:203], v[28:31]
	v_mfma_f32_16x16x32_bf16 v[24:27], v[160:163], v[200:203], v[24:27]
	v_mfma_f32_16x16x32_bf16 v[12:15], v[144:147], v[208:211], v[12:15]
	v_mfma_f32_16x16x32_bf16 v[8:11], v[160:163], v[208:211], v[8:11]
	v_mfma_f32_16x16x32_bf16 v[60:63], v[156:159], v[188:191], v[60:63]
	v_mfma_f32_16x16x32_bf16 v[56:59], v[164:167], v[188:191], v[56:59]
	v_mfma_f32_16x16x32_bf16 v[44:47], v[156:159], v[196:199], v[44:47]
	v_mfma_f32_16x16x32_bf16 v[40:43], v[164:167], v[196:199], v[40:43]
	v_mfma_f32_16x16x32_bf16 v[28:31], v[156:159], v[204:207], v[28:31]
	v_mfma_f32_16x16x32_bf16 v[24:27], v[164:167], v[204:207], v[24:27]
	v_mfma_f32_16x16x32_bf16 v[12:15], v[156:159], v[212:215], v[12:15]
	v_mfma_f32_16x16x32_bf16 v[8:11], v[164:167], v[212:215], v[8:11]
	v_mfma_f32_16x16x32_bf16 v[52:55], v[168:171], v[184:187], v[52:55]
	v_mfma_f32_16x16x32_bf16 v[48:51], v[176:179], v[184:187], v[48:51]
	v_mfma_f32_16x16x32_bf16 v[36:39], v[168:171], v[192:195], v[36:39]
	v_mfma_f32_16x16x32_bf16 v[32:35], v[176:179], v[192:195], v[32:35]
	v_mfma_f32_16x16x32_bf16 v[20:23], v[168:171], v[200:203], v[20:23]
	v_mfma_f32_16x16x32_bf16 v[16:19], v[176:179], v[200:203], v[16:19]
	v_mfma_f32_16x16x32_bf16 v[4:7], v[168:171], v[208:211], v[4:7]
	v_mfma_f32_16x16x32_bf16 v[0:3], v[176:179], v[208:211], v[0:3]
	v_mfma_f32_16x16x32_bf16 v[52:55], v[172:175], v[188:191], v[52:55]
	v_mfma_f32_16x16x32_bf16 v[48:51], v[180:183], v[188:191], v[48:51]
	v_mfma_f32_16x16x32_bf16 v[36:39], v[172:175], v[196:199], v[36:39]
	v_mfma_f32_16x16x32_bf16 v[32:35], v[180:183], v[196:199], v[32:35]
	v_mfma_f32_16x16x32_bf16 v[20:23], v[172:175], v[204:207], v[20:23]
	v_mfma_f32_16x16x32_bf16 v[16:19], v[180:183], v[204:207], v[16:19]
	v_mfma_f32_16x16x32_bf16 v[4:7], v[172:175], v[212:215], v[4:7]
	v_mfma_f32_16x16x32_bf16 v[0:3], v[180:183], v[212:215], v[0:3]
	s_barrier
	s_mov_b64 s[26:27], s[28:29]
	s_cbranch_scc0 .LBB0_1077
	s_setprio 0
	s_and_b64 vcc, exec, s[12:13]
	s_cbranch_vccz .LBB0_1080
	s_barrier

.Lmy_prio_skip7:
.LBB0_1313:
	ds_read_b128 v[48:51], v163
	ds_read_b128 v[52:55], v163 offset:1024
	ds_read_b128 v[152:155], v163 offset:2048
	ds_read_b128 v[156:159], v163 offset:3072
	ds_read_b128 v[168:171], v164
	ds_read_b128 v[172:175], v164 offset:1024
	ds_read_b128 v[176:179], v164 offset:2048
	ds_read_b128 v[180:183], v164 offset:3072
	s_add_u32 s42, s40, 0xfff00080
	s_addc_u32 s43, s41, -1
	s_cmp_eq_u32 s60, 60
	s_cselect_b32 s45, s14, s43
	s_cselect_b32 s44, s29, s42
	s_cselect_b32 s43, s27, s35
	s_cselect_b32 s42, s39, s34
	s_add_i32 m0, s47, 0xc000
	ds_read_b128 v[184:187], v165
	ds_read_b128 v[188:191], v165 offset:1024
	ds_read_b128 v[192:195], v165 offset:2048
	ds_read_b128 v[196:199], v165 offset:3072
	ds_read_b128 v[200:203], v165 offset:4096
	ds_read_b128 v[204:207], v165 offset:5120
	ds_read_b128 v[208:211], v165 offset:6144
	ds_read_b128 v[212:215], v165 offset:7168
	global_load_lds_dwordx4 v144, s[40:41]
	s_add_i32 m0, s47, 0xe000
	s_nop 0
	global_load_lds_dwordx4 v146, s[40:41]
	s_waitcnt vmcnt(8)
	s_waitcnt lgkmcnt(0)
	s_barrier
	s_waitcnt lgkmcnt(0)
	v_mfma_f32_16x16x32_bf16 v[44:47], v[48:51], v[184:187], v[44:47]
	v_mfma_f32_16x16x32_bf16 v[40:43], v[152:155], v[184:187], v[40:43]
	v_mfma_f32_16x16x32_bf16 v[124:127], v[48:51], v[192:195], v[124:127]
	v_mfma_f32_16x16x32_bf16 v[120:123], v[152:155], v[192:195], v[120:123]
	v_mfma_f32_16x16x32_bf16 v[108:111], v[48:51], v[200:203], v[108:111]
	v_mfma_f32_16x16x32_bf16 v[104:107], v[152:155], v[200:203], v[104:107]
	v_mfma_f32_16x16x32_bf16 v[92:95], v[48:51], v[208:211], v[92:95]
	v_mfma_f32_16x16x32_bf16 v[88:91], v[152:155], v[208:211], v[88:91]
	v_mfma_f32_16x16x32_bf16 v[44:47], v[52:55], v[188:191], v[44:47]
	v_mfma_f32_16x16x32_bf16 v[40:43], v[156:159], v[188:191], v[40:43]
	v_mfma_f32_16x16x32_bf16 v[124:127], v[52:55], v[196:199], v[124:127]
	v_mfma_f32_16x16x32_bf16 v[120:123], v[156:159], v[196:199], v[120:123]
	v_mfma_f32_16x16x32_bf16 v[108:111], v[52:55], v[204:207], v[108:111]
	v_mfma_f32_16x16x32_bf16 v[104:107], v[156:159], v[204:207], v[104:107]
	v_mfma_f32_16x16x32_bf16 v[92:95], v[52:55], v[212:215], v[92:95]
	v_mfma_f32_16x16x32_bf16 v[88:91], v[156:159], v[212:215], v[88:91]
	v_mfma_f32_16x16x32_bf16 v[132:135], v[168:171], v[184:187], v[132:135]
	v_mfma_f32_16x16x32_bf16 v[128:131], v[176:179], v[184:187], v[128:131]
	v_mfma_f32_16x16x32_bf16 v[116:119], v[168:171], v[192:195], v[116:119]
	v_mfma_f32_16x16x32_bf16 v[112:115], v[176:179], v[192:195], v[112:115]
	v_mfma_f32_16x16x32_bf16 v[100:103], v[168:171], v[200:203], v[100:103]
	v_mfma_f32_16x16x32_bf16 v[96:99], v[176:179], v[200:203], v[96:99]
	v_mfma_f32_16x16x32_bf16 v[84:87], v[168:171], v[208:211], v[84:87]
	v_mfma_f32_16x16x32_bf16 v[80:83], v[176:179], v[208:211], v[80:83]
	v_mfma_f32_16x16x32_bf16 v[132:135], v[172:175], v[188:191], v[132:135]
	v_mfma_f32_16x16x32_bf16 v[128:131], v[180:183], v[188:191], v[128:131]
	v_mfma_f32_16x16x32_bf16 v[116:119], v[172:175], v[196:199], v[116:119]
	v_mfma_f32_16x16x32_bf16 v[112:115], v[180:183], v[196:199], v[112:115]
	v_mfma_f32_16x16x32_bf16 v[100:103], v[172:175], v[204:207], v[100:103]
	v_mfma_f32_16x16x32_bf16 v[96:99], v[180:183], v[204:207], v[96:99]
	v_mfma_f32_16x16x32_bf16 v[84:87], v[172:175], v[212:215], v[84:87]
	v_mfma_f32_16x16x32_bf16 v[80:83], v[180:183], v[212:215], v[80:83]
	s_barrier
	s_add_i32 s61, s56, s46
	s_mov_b32 m0, s61
	ds_read_b128 v[184:187], v165 offset:16384
	ds_read_b128 v[188:191], v165 offset:17408
	ds_read_b128 v[192:195], v165 offset:18432
	ds_read_b128 v[196:199], v165 offset:19456
	ds_read_b128 v[200:203], v165 offset:20480
	ds_read_b128 v[204:207], v165 offset:21504
	ds_read_b128 v[208:211], v165 offset:22528
	ds_read_b128 v[212:215], v165 offset:23552
	global_load_lds_dwordx4 v138, s[42:43]
	s_add_i32 m0, s61, 0x2000
	s_add_u32 s62, s42, 0x100000
	v_lshl_add_u64 v[218:219], s[42:43], 0, v[142:143]
	s_addc_u32 s63, s43, 0
	s_add_i32 s61, s57, s46
	global_load_lds_dwordx4 v142, s[42:43]
	s_mov_b32 m0, s61
	v_lshl_add_u64 v[222:223], s[44:45], 0, v[140:141]
	global_load_lds_dwordx4 v138, s[62:63]
	s_add_i32 m0, s61, 0x2000
	s_nop 0
	global_load_lds_dwordx4 v142, s[62:63]
	v_lshl_add_u64 v[220:221], s[44:45], 0, v[136:137]
	s_mov_b32 m0, s47
	s_nop 0
	global_load_lds_dwordx4 v136, s[44:45]
	s_mov_b32 m0, s48
	s_nop 0
	global_load_lds_dwordx4 v140, s[44:45]
	s_waitcnt vmcnt(8)
	s_waitcnt lgkmcnt(0)
	s_barrier
	s_waitcnt lgkmcnt(0)
	v_mfma_f32_16x16x32_bf16 v[76:79], v[48:51], v[184:187], v[76:79]
	v_mfma_f32_16x16x32_bf16 v[72:75], v[152:155], v[184:187], v[72:75]
	v_mfma_f32_16x16x32_bf16 v[60:63], v[48:51], v[192:195], v[60:63]
	v_mfma_f32_16x16x32_bf16 v[56:59], v[152:155], v[192:195], v[56:59]
	v_mfma_f32_16x16x32_bf16 v[28:31], v[48:51], v[200:203], v[28:31]
	v_mfma_f32_16x16x32_bf16 v[24:27], v[152:155], v[200:203], v[24:27]
	v_mfma_f32_16x16x32_bf16 v[12:15], v[48:51], v[208:211], v[12:15]
	v_mfma_f32_16x16x32_bf16 v[8:11], v[152:155], v[208:211], v[8:11]
	v_mfma_f32_16x16x32_bf16 v[76:79], v[52:55], v[188:191], v[76:79]
	v_mfma_f32_16x16x32_bf16 v[72:75], v[156:159], v[188:191], v[72:75]
	v_mfma_f32_16x16x32_bf16 v[60:63], v[52:55], v[196:199], v[60:63]
	v_mfma_f32_16x16x32_bf16 v[56:59], v[156:159], v[196:199], v[56:59]
	v_mfma_f32_16x16x32_bf16 v[28:31], v[52:55], v[204:207], v[28:31]
	v_mfma_f32_16x16x32_bf16 v[24:27], v[156:159], v[204:207], v[24:27]
	v_mfma_f32_16x16x32_bf16 v[12:15], v[52:55], v[212:215], v[12:15]
	v_mfma_f32_16x16x32_bf16 v[8:11], v[156:159], v[212:215], v[8:11]
	v_mfma_f32_16x16x32_bf16 v[36:39], v[168:171], v[192:195], v[36:39]
	v_mfma_f32_16x16x32_bf16 v[32:35], v[176:179], v[192:195], v[32:35]
	v_mfma_f32_16x16x32_bf16 v[20:23], v[168:171], v[200:203], v[20:23]
	v_mfma_f32_16x16x32_bf16 v[16:19], v[176:179], v[200:203], v[16:19]
	v_mfma_f32_16x16x32_bf16 v[4:7], v[168:171], v[208:211], v[4:7]
	v_mfma_f32_16x16x32_bf16 v[0:3], v[176:179], v[208:211], v[0:3]
	v_mfma_f32_16x16x32_bf16 v[48:51], v[168:171], v[184:187], v[68:71]
	v_mfma_f32_16x16x32_bf16 v[52:55], v[176:179], v[184:187], v[64:67]
	v_mfma_f32_16x16x32_bf16 v[36:39], v[172:175], v[196:199], v[36:39]
	v_mfma_f32_16x16x32_bf16 v[32:35], v[180:183], v[196:199], v[32:35]
	v_mfma_f32_16x16x32_bf16 v[20:23], v[172:175], v[204:207], v[20:23]
	v_mfma_f32_16x16x32_bf16 v[16:19], v[180:183], v[204:207], v[16:19]
	v_mfma_f32_16x16x32_bf16 v[4:7], v[172:175], v[212:215], v[4:7]
	v_mfma_f32_16x16x32_bf16 v[0:3], v[180:183], v[212:215], v[0:3]
	v_mfma_f32_16x16x32_bf16 v[48:51], v[172:175], v[188:191], v[48:51]
	v_mfma_f32_16x16x32_bf16 v[52:55], v[180:183], v[188:191], v[52:55]
	s_barrier
	s_add_i32 s61, 0, 0x18000
	s_add_i32 s62, 0, 0x1c000
	v_add_u32_e32 v156, s61, v161
	v_add_u32_e32 v167, s62, v161
	ds_read_b128 v[64:67], v156
	ds_read_b128 v[68:71], v156 offset:1024
	ds_read_b128 v[152:155], v156 offset:2048
	ds_read_b128 v[156:159], v156 offset:3072
	ds_read_b128 v[168:171], v167
	ds_read_b128 v[172:175], v167 offset:1024
	ds_read_b128 v[176:179], v167 offset:2048
	ds_read_b128 v[180:183], v167 offset:3072
	s_add_u32 s44, s44, 0x100000
	s_addc_u32 s45, s45, 0
	s_mov_b32 m0, s49
	ds_read_b128 v[184:187], v165 offset:32768
	ds_read_b128 v[188:191], v165 offset:33792
	ds_read_b128 v[192:195], v165 offset:34816
	ds_read_b128 v[196:199], v165 offset:35840
	ds_read_b128 v[200:203], v165 offset:36864
	ds_read_b128 v[204:207], v165 offset:37888
	ds_read_b128 v[208:211], v165 offset:38912
	ds_read_b128 v[212:215], v165 offset:39936
	global_load_lds_dwordx4 v136, s[44:45]
	s_mov_b32 m0, s50
	s_nop 0
	global_load_lds_dwordx4 v140, s[44:45]
	s_waitcnt vmcnt(8)
	s_waitcnt lgkmcnt(0)
	s_barrier
	s_waitcnt lgkmcnt(0)
	v_mfma_f32_16x16x32_bf16 v[44:47], v[64:67], v[184:187], v[44:47]
	v_mfma_f32_16x16x32_bf16 v[40:43], v[152:155], v[184:187], v[40:43]
	v_mfma_f32_16x16x32_bf16 v[124:127], v[64:67], v[192:195], v[124:127]
	v_mfma_f32_16x16x32_bf16 v[120:123], v[152:155], v[192:195], v[120:123]
	v_mfma_f32_16x16x32_bf16 v[108:111], v[64:67], v[200:203], v[108:111]
	v_mfma_f32_16x16x32_bf16 v[104:107], v[152:155], v[200:203], v[104:107]
	v_mfma_f32_16x16x32_bf16 v[92:95], v[64:67], v[208:211], v[92:95]
	v_mfma_f32_16x16x32_bf16 v[88:91], v[152:155], v[208:211], v[88:91]
	v_mfma_f32_16x16x32_bf16 v[44:47], v[68:71], v[188:191], v[44:47]
	v_mfma_f32_16x16x32_bf16 v[40:43], v[156:159], v[188:191], v[40:43]
	v_mfma_f32_16x16x32_bf16 v[124:127], v[68:71], v[196:199], v[124:127]
	v_mfma_f32_16x16x32_bf16 v[120:123], v[156:159], v[196:199], v[120:123]
	v_mfma_f32_16x16x32_bf16 v[108:111], v[68:71], v[204:207], v[108:111]
	v_mfma_f32_16x16x32_bf16 v[104:107], v[156:159], v[204:207], v[104:107]
	v_mfma_f32_16x16x32_bf16 v[92:95], v[68:71], v[212:215], v[92:95]
	v_mfma_f32_16x16x32_bf16 v[88:91], v[156:159], v[212:215], v[88:91]
	v_mfma_f32_16x16x32_bf16 v[132:135], v[168:171], v[184:187], v[132:135]
	v_mfma_f32_16x16x32_bf16 v[128:131], v[176:179], v[184:187], v[128:131]
	v_mfma_f32_16x16x32_bf16 v[116:119], v[168:171], v[192:195], v[116:119]
	v_mfma_f32_16x16x32_bf16 v[112:115], v[176:179], v[192:195], v[112:115]
	v_mfma_f32_16x16x32_bf16 v[100:103], v[168:171], v[200:203], v[100:103]
	v_mfma_f32_16x16x32_bf16 v[96:99], v[176:179], v[200:203], v[96:99]
	v_mfma_f32_16x16x32_bf16 v[84:87], v[168:171], v[208:211], v[84:87]
	v_mfma_f32_16x16x32_bf16 v[80:83], v[176:179], v[208:211], v[80:83]
	v_mfma_f32_16x16x32_bf16 v[132:135], v[172:175], v[188:191], v[132:135]
	v_mfma_f32_16x16x32_bf16 v[128:131], v[180:183], v[188:191], v[128:131]
	v_mfma_f32_16x16x32_bf16 v[116:119], v[172:175], v[196:199], v[116:119]
	v_mfma_f32_16x16x32_bf16 v[112:115], v[180:183], v[196:199], v[112:115]
	v_mfma_f32_16x16x32_bf16 v[100:103], v[172:175], v[204:207], v[100:103]
	v_mfma_f32_16x16x32_bf16 v[96:99], v[180:183], v[204:207], v[96:99]
	v_mfma_f32_16x16x32_bf16 v[84:87], v[172:175], v[212:215], v[84:87]
	v_mfma_f32_16x16x32_bf16 v[80:83], v[180:183], v[212:215], v[80:83]
	s_barrier
	s_add_i32 s44, s61, s46
	s_mov_b32 m0, s44
	ds_read_b128 v[184:187], v165 offset:49152
	ds_read_b128 v[188:191], v165 offset:50176
	ds_read_b128 v[192:195], v165 offset:51200
	ds_read_b128 v[196:199], v165 offset:52224
	ds_read_b128 v[200:203], v165 offset:53248
	ds_read_b128 v[204:207], v165 offset:54272
	ds_read_b128 v[208:211], v165 offset:55296
	ds_read_b128 v[212:215], v165 offset:56320
	s_add_u32 s100, s42, 0x80
	s_addc_u32 s101, s43, 0
	global_load_lds_dwordx4 v138, s[100:101]
	s_add_i32 m0, s44, 0x2000
	s_add_u32 s42, s42, 0x100080
	v_lshl_add_u64 v[216:217], v[218:219], 0, s[22:23]
	s_addc_u32 s43, s43, 0
	s_add_i32 s44, s62, s46
	global_load_lds_dwordx4 v[216:217], off
	s_mov_b32 m0, s44
	s_nop 0
	global_load_lds_dwordx4 v138, s[42:43]
	s_add_i32 m0, s44, 0x2000
	s_nop 0
	global_load_lds_dwordx4 v142, s[42:43]
	v_lshl_add_u64 v[216:217], v[220:221], 0, s[22:23]
	s_mov_b32 m0, s52
	s_nop 0
	global_load_lds_dwordx4 v[216:217], off
	v_lshl_add_u64 v[216:217], v[222:223], 0, s[22:23]
	s_mov_b32 m0, s53
	s_nop 0
	global_load_lds_dwordx4 v[216:217], off
	s_add_i32 s60, s60, 2
	s_add_u32 s40, s40, 0x100
	s_addc_u32 s41, s41, 0
	s_add_u32 s34, s34, 0x100
	s_addc_u32 s35, s35, 0
	s_cmp_gt_u32 s60, 61
	s_waitcnt vmcnt(8)
	s_waitcnt lgkmcnt(0)
	s_barrier
	s_waitcnt lgkmcnt(0)
	v_mfma_f32_16x16x32_bf16 v[76:79], v[64:67], v[184:187], v[76:79]
	v_mfma_f32_16x16x32_bf16 v[72:75], v[152:155], v[184:187], v[72:75]
	v_mfma_f32_16x16x32_bf16 v[60:63], v[64:67], v[192:195], v[60:63]
	v_mfma_f32_16x16x32_bf16 v[56:59], v[152:155], v[192:195], v[56:59]
	v_mfma_f32_16x16x32_bf16 v[28:31], v[64:67], v[200:203], v[28:31]
	v_mfma_f32_16x16x32_bf16 v[24:27], v[152:155], v[200:203], v[24:27]
	v_mfma_f32_16x16x32_bf16 v[12:15], v[64:67], v[208:211], v[12:15]
	v_mfma_f32_16x16x32_bf16 v[8:11], v[152:155], v[208:211], v[8:11]
	v_mfma_f32_16x16x32_bf16 v[76:79], v[68:71], v[188:191], v[76:79]
	v_mfma_f32_16x16x32_bf16 v[72:75], v[156:159], v[188:191], v[72:75]
	v_mfma_f32_16x16x32_bf16 v[60:63], v[68:71], v[196:199], v[60:63]
	v_mfma_f32_16x16x32_bf16 v[56:59], v[156:159], v[196:199], v[56:59]
	v_mfma_f32_16x16x32_bf16 v[28:31], v[68:71], v[204:207], v[28:31]
	v_mfma_f32_16x16x32_bf16 v[24:27], v[156:159], v[204:207], v[24:27]
	v_mfma_f32_16x16x32_bf16 v[12:15], v[68:71], v[212:215], v[12:15]
	v_mfma_f32_16x16x32_bf16 v[8:11], v[156:159], v[212:215], v[8:11]
	v_mfma_f32_16x16x32_bf16 v[48:51], v[168:171], v[184:187], v[48:51]
	v_mfma_f32_16x16x32_bf16 v[68:71], v[172:175], v[188:191], v[48:51]
	v_mfma_f32_16x16x32_bf16 v[48:51], v[176:179], v[184:187], v[52:55]
	v_mfma_f32_16x16x32_bf16 v[36:39], v[168:171], v[192:195], v[36:39]
	v_mfma_f32_16x16x32_bf16 v[32:35], v[176:179], v[192:195], v[32:35]
	v_mfma_f32_16x16x32_bf16 v[20:23], v[168:171], v[200:203], v[20:23]
	v_mfma_f32_16x16x32_bf16 v[16:19], v[176:179], v[200:203], v[16:19]
	v_mfma_f32_16x16x32_bf16 v[4:7], v[168:171], v[208:211], v[4:7]
	v_mfma_f32_16x16x32_bf16 v[0:3], v[176:179], v[208:211], v[0:3]
	v_mfma_f32_16x16x32_bf16 v[64:67], v[180:183], v[188:191], v[48:51]
	v_mfma_f32_16x16x32_bf16 v[36:39], v[172:175], v[196:199], v[36:39]
	v_mfma_f32_16x16x32_bf16 v[32:35], v[180:183], v[196:199], v[32:35]
	v_mfma_f32_16x16x32_bf16 v[20:23], v[172:175], v[204:207], v[20:23]
	v_mfma_f32_16x16x32_bf16 v[16:19], v[180:183], v[204:207], v[16:19]
	v_mfma_f32_16x16x32_bf16 v[4:7], v[172:175], v[212:215], v[4:7]
	v_mfma_f32_16x16x32_bf16 v[0:3], v[180:183], v[212:215], v[0:3]
	s_barrier
	s_cbranch_scc0 .LBB0_1313
	s_setprio 0
	s_and_b64 vcc, exec, s[24:25]
	s_cbranch_vccz .LBB0_1316
	s_barrier
